# GEMM K-loops: first iteration peeled with srcC=0 on the first MFMA of each accumulator, the 128-v_mov accumulator zeroing per unit removed (6 GEMM sites); stacked on v22
# speedup vs baseline: 1.0317x; 1.0121x over previous
; #define PG8_STAGE_A1(bufoff, gbase) do { if (Epi::GATHER) PG8_STAGE(bufoff, gbase, voffA[1]); else PG8_STAGE(bufoff, (gbase) + hstep, voffA[0]); } while (0)
; #define PG8_WAIT_V(n) asm volatile("s_waitcnt vmcnt(" #n ")" ::: "memory")
; template <class Epi, class Sched>
; __device__ __forceinline__ void gemm_phase(const int tid, LAS unsigned char* lds, const bf16* Aop, const bf16* Bop, const int K_, const Sched& S, const Epi& E, const bf16* Aop1 = nullptr, const bf16* Bop1 = nullptr) {
;     ...
;         for (int t = 0; t < nt; t += 2) {
;             const bool last = (t == nt - 2);
;             const char* a1 = cA + (size_t)(t + 1) * kstep;
;             const char* a2 = last ? nA : cA + (size_t)(t + 2) * kstep; const char* b2 = last ? nB : cB + (size_t)(t + 2) * kstep;
;             const char* a3 = a2 + kstep; const char* b3 = b2 + kstep;
;             PG8_LDB(B0, 0, 0); PG8_LDB(B1, 0, 1); PG8_SCHED; PG8_LDA(At, 0, 0); PG8_STAGE_A1(PG8_SA(1, 1), a1);
;             PG8_WAIT_V(8); PG8_WAIT_L(0); PG8_BAR; PG8_MMA(0, 0, At, B0); PG8_MMA(0, 1, At, B1); PG8_BAR; PG8_SCHED;
;             PG8_LDA(At, 0, 1); PG8_STAGE(PG8_SB(0, 0), b2, voffB); PG8_STAGE(PG8_SB(0, 1), b2 + hstep, voffB); if (Epi::GATHER && last && has_next) PG8_GOFFS((ui + 1) & 1); PG8_STAGE(PG8_SA(0, 0), a2, voffA[0]);
;             PG8_WAIT_V(8); PG8_WAIT_L(0); PG8_BAR; PG8_MMA(1, 0, At, B0); PG8_MMA(1, 1, At, B1); PG8_BAR; PG8_SCHED;
;             PG8_LDB(B0, 1, 0); PG8_LDB(B1, 1, 1); PG8_SCHED; PG8_LDA(At, 1, 0); PG8_STAGE_A1(PG8_SA(0, 1), a2);
;             PG8_WAIT_V(8); PG8_WAIT_L(0); PG8_BAR; PG8_MMA(0, 0, At, B0); PG8_MMA(0, 1, At, B1); PG8_BAR; PG8_SCHED;
;             PG8_LDA(At, 1, 1); PG8_STAGE(PG8_SB(1, 0), b3, voffB); PG8_STAGE(PG8_SB(1, 1), b3 + hstep, voffB); PG8_STAGE(PG8_SA(1, 0), a3, voffA[0]);
;             PG8_WAIT_V(8); PG8_WAIT_L(0); PG8_BAR; PG8_MMA(1, 0, At, B0); PG8_MMA(1, 1, At, B1); PG8_BAR; PG8_SCHED;
;         }
;         if (wr == 0) PG8_BAR;
;         E(acc, cur, wr, wc, fr, fq);
;         if (!has_next) break;
; #pragma unroll
;         for (int a = 0; a < 2; ++a)
; #pragma unroll
;             for (int b = 0; b < 2; ++b)
; #pragma unroll
;                 for (int m = 0; m < 4; ++m)
; #pragma unroll
;                     for (int n = 0; n < 2; ++n) acc[a][b][m][n] = (f32x4){0.f, 0.f, 0.f, 0.f};
;         cur = nxt; cA = nA; cB = nB; ++ui;
.LBB0_129:
	v_mov_b32_e32 v143, 0
	s_andn2_b64 vcc, exec, s[18:19]
	s_cbranch_vccnz .LBB0_133
	s_add_u32 s26, s26, 0x80
	s_addc_u32 s27, s27, 0
	s_add_u32 s11, s42, 0x100
	v_mov_b64_e32 v[180:181], v[178:179]
	v_mov_b64_e32 v[178:179], v[176:177]
	v_mov_b64_e32 v[176:177], v[190:191]
	v_mov_b32_e32 v205, 0x7f800000
	v_mov_b32_e32 v203, 0x3ecc95a3
	v_mov_b32_e32 v200, 1
	v_mov_b64_e32 v[226:227], 0x100
	s_addc_u32 s42, s43, 0
	s_mov_b32 s40, 0
	s_add_i32 s43, s40, 2
	s_add_u32 s44, s26, 0x80
	s_addc_u32 s41, s27, 0
	s_add_i32 s48, 0, 0x10000
	s_cmp_eq_u32 s77, s40
	s_cselect_b32 s41, s35, s41
	s_cselect_b32 s40, s34, s44
	s_cselect_b32 s45, s37, s42
	s_cselect_b32 s44, s36, s11
	s_add_i32 s49, 0, 0x14000
	v_add_u32_e32 v80, s48, v3
	v_add_u32_e32 v160, s49, v3
	ds_read_b128 v[60:63], v80
	ds_read_b128 v[68:71], v80 offset:1024
	ds_read_b128 v[76:79], v80 offset:2048
	ds_read_b128 v[80:83], v80 offset:3072
	ds_read_b128 v[148:151], v160
	ds_read_b128 v[152:155], v160 offset:1024
	ds_read_b128 v[156:159], v160 offset:2048
	ds_read_b128 v[160:163], v160 offset:3072
	v_lshl_add_u64 v[164:165], s[26:27], 0, v[192:193]
	s_add_i32 m0, s70, 0xc000
	ds_read_b128 v[206:209], v175
	ds_read_b128 v[210:213], v175 offset:1024
	ds_read_b128 v[214:217], v175 offset:2048
	ds_read_b128 v[218:221], v175 offset:3072
	ds_read_b128 v[238:241], v175 offset:4096
	ds_read_b128 v[242:245], v175 offset:5120
	ds_read_b128 v[246:249], v175 offset:6144
	ds_read_b128 v[230:233], v175 offset:7168
	global_load_lds_dwordx4 v[164:165], off
	v_lshl_add_u64 v[164:165], s[26:27], 0, v[194:195]
	s_add_i32 m0, s70, 0xe000
	s_nop 0
	global_load_lds_dwordx4 v[164:165], off
	s_waitcnt vmcnt(8)
	s_waitcnt lgkmcnt(0)
	s_barrier
	s_setprio 1
	s_waitcnt lgkmcnt(0)
	v_mfma_f32_16x16x32_bf16 v[140:143], v[60:63], v[206:209], 0
	v_mfma_f32_16x16x32_bf16 v[144:147], v[76:79], v[206:209], 0
	v_mfma_f32_16x16x32_bf16 v[128:131], v[60:63], v[214:217], 0
	v_mfma_f32_16x16x32_bf16 v[124:127], v[76:79], v[214:217], 0
	v_mfma_f32_16x16x32_bf16 v[112:115], v[60:63], v[238:241], 0
	v_mfma_f32_16x16x32_bf16 v[108:111], v[76:79], v[238:241], 0
	v_mfma_f32_16x16x32_bf16 v[96:99], v[60:63], v[246:249], 0
	v_mfma_f32_16x16x32_bf16 v[92:95], v[76:79], v[246:249], 0
	v_mfma_f32_16x16x32_bf16 v[140:143], v[68:71], v[210:213], v[140:143]
	v_mfma_f32_16x16x32_bf16 v[144:147], v[80:83], v[210:213], v[144:147]
	v_mfma_f32_16x16x32_bf16 v[128:131], v[68:71], v[218:221], v[128:131]
	v_mfma_f32_16x16x32_bf16 v[124:127], v[80:83], v[218:221], v[124:127]
	v_mfma_f32_16x16x32_bf16 v[112:115], v[68:71], v[242:245], v[112:115]
	v_mfma_f32_16x16x32_bf16 v[108:111], v[80:83], v[242:245], v[108:111]
	v_mfma_f32_16x16x32_bf16 v[96:99], v[68:71], v[230:233], v[96:99]
	v_mfma_f32_16x16x32_bf16 v[92:95], v[80:83], v[230:233], v[92:95]
	s_setprio 0
	s_setprio 1
	v_mfma_f32_16x16x32_bf16 v[136:139], v[148:151], v[206:209], 0
	v_mfma_f32_16x16x32_bf16 v[132:135], v[156:159], v[206:209], 0
	v_mfma_f32_16x16x32_bf16 v[120:123], v[148:151], v[214:217], 0
	v_mfma_f32_16x16x32_bf16 v[116:119], v[156:159], v[214:217], 0
	v_mfma_f32_16x16x32_bf16 v[104:107], v[148:151], v[238:241], 0
	v_mfma_f32_16x16x32_bf16 v[100:103], v[156:159], v[238:241], 0
	v_mfma_f32_16x16x32_bf16 v[88:91], v[148:151], v[246:249], 0
	v_mfma_f32_16x16x32_bf16 v[84:87], v[156:159], v[246:249], 0
	v_mfma_f32_16x16x32_bf16 v[136:139], v[152:155], v[210:213], v[136:139]
	v_mfma_f32_16x16x32_bf16 v[132:135], v[160:163], v[210:213], v[132:135]
	v_mfma_f32_16x16x32_bf16 v[120:123], v[152:155], v[218:221], v[120:123]
	v_mfma_f32_16x16x32_bf16 v[116:119], v[160:163], v[218:221], v[116:119]
	v_mfma_f32_16x16x32_bf16 v[104:107], v[152:155], v[242:245], v[104:107]
	v_mfma_f32_16x16x32_bf16 v[100:103], v[160:163], v[242:245], v[100:103]
	v_mfma_f32_16x16x32_bf16 v[88:91], v[152:155], v[230:233], v[88:91]
	v_mfma_f32_16x16x32_bf16 v[84:87], v[160:163], v[230:233], v[84:87]
	s_setprio 0
	s_barrier
	s_add_i32 s48, s48, s69
	v_lshl_add_u64 v[164:165], s[44:45], 0, v[166:167]
	s_mov_b32 m0, s48
	ds_read_b128 v[206:209], v175 offset:16384
	ds_read_b128 v[210:213], v175 offset:17408
	ds_read_b128 v[214:217], v175 offset:18432
	ds_read_b128 v[218:221], v175 offset:19456
	ds_read_b128 v[230:233], v175 offset:20480
	ds_read_b128 v[238:241], v175 offset:21504
	ds_read_b128 v[242:245], v175 offset:22528
	ds_read_b128 v[246:249], v175 offset:23552
	global_load_lds_dwordx4 v[164:165], off
	s_add_i32 m0, s48, 0x2000
	v_lshl_add_u64 v[222:223], s[44:45], 0, v[170:171]
	s_add_u32 s44, s44, s6
	s_addc_u32 s45, s45, s7
	s_add_i32 s48, s49, s69
	global_load_lds_dwordx4 v[222:223], off
	v_lshl_add_u64 v[250:251], s[44:45], 0, v[166:167]
	s_mov_b32 m0, s48
	v_lshl_add_u64 v[196:197], s[44:45], 0, v[170:171]
	global_load_lds_dwordx4 v[250:251], off
	s_add_i32 m0, s48, 0x2000
	v_lshl_add_u64 v[198:199], s[40:41], 0, v[0:1]
	global_load_lds_dwordx4 v[196:197], off
	s_mov_b32 m0, s70
	v_lshl_add_u64 v[224:225], s[40:41], 0, v[168:169]
	global_load_lds_dwordx4 v[198:199], off
	s_mov_b32 m0, s71
	s_nop 0
	global_load_lds_dwordx4 v[224:225], off
	s_waitcnt vmcnt(8)
	s_waitcnt lgkmcnt(0)
	s_barrier
; #define PG8_GOFFS(slot_) do { _Pragma("unroll") for (int _i = 0; _i < 2; ++_i) { int R, C; stage_rc(tid * 16 + _i * 8192, R, C); _Pragma("unroll") for (int _h = 0; _h < 2; ++_h) { \
;         unsigned t_ = gtab[(slot_) * 256 + R + 128 * _h]; t_ = t_ < (unsigned)(T - 1) ? t_ : (unsigned)(T - 1); voffA[_h][_i] = (t_ * (unsigned)K + (unsigned)C) * 2u; } } } while (0)
; #define PG8_STAGE(bufoff, gbase, voff) do { _Pragma("unroll") for (int _i = 0; _i < 2; ++_i) \
;         __builtin_amdgcn_global_load_lds((const unsigned*)((const char*)(gbase) + (voff)[_i]), (LAS unsigned*)(lds + (bufoff) + ldsw + _i * 8192), 16, 0, 0); } while (0)
; #define PG8_STAGE_A1(bufoff, gbase) do { if (Epi::GATHER) PG8_STAGE(bufoff, gbase, voffA[1]); else PG8_STAGE(bufoff, (gbase) + hstep, voffA[0]); } while (0)
; #define PG8_LDA(dst, b, h) do { _Pragma("unroll") for (int m = 0; m < 4; ++m) _Pragma("unroll") for (int k = 0; k < 2; ++k) dst[m][k] = *(const LAS bf16x8*)(lds + PG8_SA(b, h) + aoff + m * 2048 + k * 1024); } while (0)
; #define PG8_LDB(dst, b, h) do { _Pragma("unroll") for (int n = 0; n < 2; ++n) _Pragma("unroll") for (int k = 0; k < 2; ++k) dst[n][k] = *(const LAS bf16x8*)(lds + PG8_SB(b, h) + boff + n * 2048 + k * 1024); } while (0)
; #define PG8_WAIT_V(n) asm volatile("s_waitcnt vmcnt(" #n ")" ::: "memory")
; #define PG8_WAIT_L(n) asm volatile("s_waitcnt lgkmcnt(" #n ")" ::: "memory")
; #define PG8_BAR __builtin_amdgcn_s_barrier()
; template <class Epi, class Sched>
; __device__ __forceinline__ void gemm_phase(const int tid, LAS unsigned char* lds, const bf16* Aop, const bf16* Bop, const int K_, const Sched& S, const Epi& E, const bf16* Aop1 = nullptr, const bf16* Bop1 = nullptr) {
;     ...
;             PG8_WAIT_V(8); PG8_WAIT_L(0); PG8_BAR; PG8_MMA(0, 0, At, B0); PG8_MMA(0, 1, At, B1); PG8_BAR; PG8_SCHED;
;             PG8_LDA(At, 0, 1); PG8_STAGE(PG8_SB(0, 0), b2, voffB); PG8_STAGE(PG8_SB(0, 1), b2 + hstep, voffB); if (Epi::GATHER && last && has_next) PG8_GOFFS((ui + 1) & 1); PG8_STAGE(PG8_SA(0, 0), a2, voffA[0]);
;             PG8_WAIT_V(8); PG8_WAIT_L(0); PG8_BAR; PG8_MMA(1, 0, At, B0); PG8_MMA(1, 1, At, B1); PG8_BAR; PG8_SCHED;
;             PG8_LDB(B0, 1, 0); PG8_LDB(B1, 1, 1); PG8_SCHED; PG8_LDA(At, 1, 0); PG8_STAGE_A1(PG8_SA(0, 1), a2);
;             PG8_WAIT_V(8); PG8_WAIT_L(0); PG8_BAR; PG8_MMA(0, 0, At, B0); PG8_MMA(0, 1, At, B1); PG8_BAR; PG8_SCHED;
	s_setprio 1
	s_waitcnt lgkmcnt(0)
	v_mfma_f32_16x16x32_bf16 v[72:75], v[60:63], v[206:209], 0
	v_mfma_f32_16x16x32_bf16 v[64:67], v[76:79], v[206:209], 0
	v_mfma_f32_16x16x32_bf16 v[48:51], v[60:63], v[214:217], 0
	v_mfma_f32_16x16x32_bf16 v[44:47], v[76:79], v[214:217], 0
	v_mfma_f32_16x16x32_bf16 v[32:35], v[60:63], v[230:233], 0
	v_mfma_f32_16x16x32_bf16 v[28:31], v[76:79], v[230:233], 0
	v_mfma_f32_16x16x32_bf16 v[16:19], v[60:63], v[242:245], 0
	v_mfma_f32_16x16x32_bf16 v[12:15], v[76:79], v[242:245], 0
	v_mfma_f32_16x16x32_bf16 v[72:75], v[68:71], v[210:213], v[72:75]
	v_mfma_f32_16x16x32_bf16 v[64:67], v[80:83], v[210:213], v[64:67]
	v_mfma_f32_16x16x32_bf16 v[48:51], v[68:71], v[218:221], v[48:51]
	v_mfma_f32_16x16x32_bf16 v[44:47], v[80:83], v[218:221], v[44:47]
	v_mfma_f32_16x16x32_bf16 v[32:35], v[68:71], v[238:241], v[32:35]
	v_mfma_f32_16x16x32_bf16 v[28:31], v[80:83], v[238:241], v[28:31]
	v_mfma_f32_16x16x32_bf16 v[16:19], v[68:71], v[246:249], v[16:19]
	v_mfma_f32_16x16x32_bf16 v[12:15], v[80:83], v[246:249], v[12:15]
	s_setprio 0
	s_setprio 1
	v_mfma_f32_16x16x32_bf16 v[56:59], v[148:151], v[206:209], 0
	v_mfma_f32_16x16x32_bf16 v[52:55], v[156:159], v[206:209], 0
	v_mfma_f32_16x16x32_bf16 v[40:43], v[148:151], v[214:217], 0
	v_mfma_f32_16x16x32_bf16 v[36:39], v[156:159], v[214:217], 0
	v_mfma_f32_16x16x32_bf16 v[24:27], v[148:151], v[230:233], 0
	v_mfma_f32_16x16x32_bf16 v[20:23], v[156:159], v[230:233], 0
	v_mfma_f32_16x16x32_bf16 v[8:11], v[148:151], v[242:245], 0
	v_mfma_f32_16x16x32_bf16 v[4:7], v[156:159], v[242:245], 0
	v_mfma_f32_16x16x32_bf16 v[56:59], v[152:155], v[210:213], v[56:59]
	v_mfma_f32_16x16x32_bf16 v[52:55], v[160:163], v[210:213], v[52:55]
	v_mfma_f32_16x16x32_bf16 v[40:43], v[152:155], v[218:221], v[40:43]
	v_mfma_f32_16x16x32_bf16 v[36:39], v[160:163], v[218:221], v[36:39]
	v_mfma_f32_16x16x32_bf16 v[24:27], v[152:155], v[238:241], v[24:27]
	v_mfma_f32_16x16x32_bf16 v[20:23], v[160:163], v[238:241], v[20:23]
	v_mfma_f32_16x16x32_bf16 v[8:11], v[152:155], v[246:249], v[8:11]
	v_mfma_f32_16x16x32_bf16 v[4:7], v[160:163], v[246:249], v[4:7]
	s_setprio 0
	s_barrier
	s_add_i32 s44, 0, 0x18000
	s_add_i32 s45, 0, 0x1c000
	v_add_u32_e32 v80, s44, v3
	v_add_u32_e32 v160, s45, v3
	ds_read_b128 v[60:63], v80
	ds_read_b128 v[68:71], v80 offset:1024
	ds_read_b128 v[76:79], v80 offset:2048
	ds_read_b128 v[80:83], v80 offset:3072
	ds_read_b128 v[148:151], v160
	ds_read_b128 v[152:155], v160 offset:1024
	ds_read_b128 v[156:159], v160 offset:2048
	ds_read_b128 v[160:163], v160 offset:3072
	s_add_u32 s40, s40, s6
	s_addc_u32 s41, s41, s7
	s_mov_b32 m0, s72
	v_lshl_add_u64 v[190:191], s[40:41], 0, v[0:1]
	ds_read_b128 v[206:209], v175 offset:32768
	ds_read_b128 v[210:213], v175 offset:33792
	ds_read_b128 v[214:217], v175 offset:34816
	ds_read_b128 v[218:221], v175 offset:35840
	ds_read_b128 v[230:233], v175 offset:36864
	ds_read_b128 v[238:241], v175 offset:37888
	ds_read_b128 v[242:245], v175 offset:38912
	ds_read_b128 v[246:249], v175 offset:39936
	global_load_lds_dwordx4 v[190:191], off
	v_lshl_add_u64 v[190:191], s[40:41], 0, v[168:169]
	s_mov_b32 m0, s73
	s_nop 0
	global_load_lds_dwordx4 v[190:191], off
	s_waitcnt vmcnt(8)
	s_waitcnt lgkmcnt(0)
	s_barrier
	s_setprio 1
	s_waitcnt lgkmcnt(0)
	v_mfma_f32_16x16x32_bf16 v[140:143], v[60:63], v[206:209], v[140:143]
	v_mfma_f32_16x16x32_bf16 v[144:147], v[76:79], v[206:209], v[144:147]
	v_mfma_f32_16x16x32_bf16 v[128:131], v[60:63], v[214:217], v[128:131]
	v_mfma_f32_16x16x32_bf16 v[124:127], v[76:79], v[214:217], v[124:127]
	v_mfma_f32_16x16x32_bf16 v[112:115], v[60:63], v[230:233], v[112:115]
	v_mfma_f32_16x16x32_bf16 v[108:111], v[76:79], v[230:233], v[108:111]
	v_mfma_f32_16x16x32_bf16 v[96:99], v[60:63], v[242:245], v[96:99]
	v_mfma_f32_16x16x32_bf16 v[92:95], v[76:79], v[242:245], v[92:95]
	v_mfma_f32_16x16x32_bf16 v[140:143], v[68:71], v[210:213], v[140:143]
	v_mfma_f32_16x16x32_bf16 v[144:147], v[80:83], v[210:213], v[144:147]
	v_mfma_f32_16x16x32_bf16 v[128:131], v[68:71], v[218:221], v[128:131]
	v_mfma_f32_16x16x32_bf16 v[124:127], v[80:83], v[218:221], v[124:127]
	v_mfma_f32_16x16x32_bf16 v[112:115], v[68:71], v[238:241], v[112:115]
	v_mfma_f32_16x16x32_bf16 v[108:111], v[80:83], v[238:241], v[108:111]
	v_mfma_f32_16x16x32_bf16 v[96:99], v[68:71], v[246:249], v[96:99]
	v_mfma_f32_16x16x32_bf16 v[92:95], v[80:83], v[246:249], v[92:95]
	s_setprio 0
	s_setprio 1
	v_mfma_f32_16x16x32_bf16 v[136:139], v[148:151], v[206:209], v[136:139]
	v_mfma_f32_16x16x32_bf16 v[132:135], v[156:159], v[206:209], v[132:135]
	v_mfma_f32_16x16x32_bf16 v[120:123], v[148:151], v[214:217], v[120:123]
	v_mfma_f32_16x16x32_bf16 v[116:119], v[156:159], v[214:217], v[116:119]
	v_mfma_f32_16x16x32_bf16 v[104:107], v[148:151], v[230:233], v[104:107]
	v_mfma_f32_16x16x32_bf16 v[100:103], v[156:159], v[230:233], v[100:103]
	v_mfma_f32_16x16x32_bf16 v[88:91], v[148:151], v[242:245], v[88:91]
	v_mfma_f32_16x16x32_bf16 v[84:87], v[156:159], v[242:245], v[84:87]
	v_mfma_f32_16x16x32_bf16 v[136:139], v[152:155], v[210:213], v[136:139]
	v_mfma_f32_16x16x32_bf16 v[132:135], v[160:163], v[210:213], v[132:135]
	v_mfma_f32_16x16x32_bf16 v[120:123], v[152:155], v[218:221], v[120:123]
	v_mfma_f32_16x16x32_bf16 v[116:119], v[160:163], v[218:221], v[116:119]
	v_mfma_f32_16x16x32_bf16 v[104:107], v[152:155], v[238:241], v[104:107]
	v_mfma_f32_16x16x32_bf16 v[100:103], v[160:163], v[238:241], v[100:103]
	v_mfma_f32_16x16x32_bf16 v[88:91], v[152:155], v[246:249], v[88:91]
	v_mfma_f32_16x16x32_bf16 v[84:87], v[160:163], v[246:249], v[84:87]
	s_setprio 0
	s_barrier
; #define PG8_GOFFS(slot_) do { _Pragma("unroll") for (int _i = 0; _i < 2; ++_i) { int R, C; stage_rc(tid * 16 + _i * 8192, R, C); _Pragma("unroll") for (int _h = 0; _h < 2; ++_h) { \
;         unsigned t_ = gtab[(slot_) * 256 + R + 128 * _h]; t_ = t_ < (unsigned)(T - 1) ? t_ : (unsigned)(T - 1); voffA[_h][_i] = (t_ * (unsigned)K + (unsigned)C) * 2u; } } } while (0)
; #define PG8_STAGE(bufoff, gbase, voff) do { _Pragma("unroll") for (int _i = 0; _i < 2; ++_i) \
;         __builtin_amdgcn_global_load_lds((const unsigned*)((const char*)(gbase) + (voff)[_i]), (LAS unsigned*)(lds + (bufoff) + ldsw + _i * 8192), 16, 0, 0); } while (0)
; #define PG8_WAIT_V(n) asm volatile("s_waitcnt vmcnt(" #n ")" ::: "memory")
; template <class Epi, class Sched>
; __device__ __forceinline__ void gemm_phase(const int tid, LAS unsigned char* lds, const bf16* Aop, const bf16* Bop, const int K_, const Sched& S, const Epi& E, const bf16* Aop1 = nullptr, const bf16* Bop1 = nullptr) {
;     ...
;         for (int t = 0; t < nt; t += 2) {
;             const bool last = (t == nt - 2);
;             const char* a1 = cA + (size_t)(t + 1) * kstep;
;             const char* a2 = last ? nA : cA + (size_t)(t + 2) * kstep; const char* b2 = last ? nB : cB + (size_t)(t + 2) * kstep;
;             const char* a3 = a2 + kstep; const char* b3 = b2 + kstep;
;             PG8_LDB(B0, 0, 0); PG8_LDB(B1, 0, 1); PG8_SCHED; PG8_LDA(At, 0, 0); PG8_STAGE_A1(PG8_SA(1, 1), a1);
;             PG8_WAIT_V(8); PG8_WAIT_L(0); PG8_BAR; PG8_MMA(0, 0, At, B0); PG8_MMA(0, 1, At, B1); PG8_BAR; PG8_SCHED;
;             PG8_LDA(At, 0, 1); PG8_STAGE(PG8_SB(0, 0), b2, voffB); PG8_STAGE(PG8_SB(0, 1), b2 + hstep, voffB); if (Epi::GATHER && last && has_next) PG8_GOFFS((ui + 1) & 1); PG8_STAGE(PG8_SA(0, 0), a2, voffA[0]);
;             PG8_WAIT_V(8); PG8_WAIT_L(0); PG8_BAR; PG8_MMA(1, 0, At, B0); PG8_MMA(1, 1, At, B1); PG8_BAR; PG8_SCHED;
;             PG8_LDB(B0, 1, 0); PG8_LDB(B1, 1, 1); PG8_SCHED; PG8_LDA(At, 1, 0); PG8_STAGE_A1(PG8_SA(0, 1), a2);
;             PG8_WAIT_V(8); PG8_WAIT_L(0); PG8_BAR; PG8_MMA(0, 0, At, B0); PG8_MMA(0, 1, At, B1); PG8_BAR; PG8_SCHED;
;             PG8_LDA(At, 1, 1); PG8_STAGE(PG8_SB(1, 0), b3, voffB); PG8_STAGE(PG8_SB(1, 1), b3 + hstep, voffB); PG8_STAGE(PG8_SA(1, 0), a3, voffA[0]);
;             PG8_WAIT_V(8); PG8_WAIT_L(0); PG8_BAR; PG8_MMA(1, 0, At, B0); PG8_MMA(1, 1, At, B1); PG8_BAR; PG8_SCHED;
	s_add_i32 s40, s44, s69
	v_lshl_add_u64 v[164:165], v[164:165], 0, s[20:21]
	s_mov_b32 m0, s40
	ds_read_b128 v[206:209], v175 offset:49152
	ds_read_b128 v[210:213], v175 offset:50176
	ds_read_b128 v[214:217], v175 offset:51200
	ds_read_b128 v[218:221], v175 offset:52224
	ds_read_b128 v[230:233], v175 offset:53248
	ds_read_b128 v[238:241], v175 offset:54272
	ds_read_b128 v[242:245], v175 offset:55296
	ds_read_b128 v[246:249], v175 offset:56320
	global_load_lds_dwordx4 v[164:165], off
	v_lshl_add_u64 v[164:165], v[222:223], 0, s[20:21]
	s_add_i32 m0, s40, 0x2000
	s_add_i32 s40, s45, s69
	global_load_lds_dwordx4 v[164:165], off
	v_lshl_add_u64 v[164:165], v[250:251], 0, s[20:21]
	s_mov_b32 m0, s40
	s_nop 0
	global_load_lds_dwordx4 v[164:165], off
	v_lshl_add_u64 v[164:165], v[196:197], 0, s[20:21]
	s_add_i32 m0, s40, 0x2000
	s_nop 0
	global_load_lds_dwordx4 v[164:165], off
	v_lshl_add_u64 v[164:165], v[198:199], 0, s[20:21]
	s_mov_b32 m0, s75
	s_nop 0
	global_load_lds_dwordx4 v[164:165], off
	v_lshl_add_u64 v[164:165], v[224:225], 0, s[20:21]
	s_mov_b32 m0, s76
	s_nop 0
	global_load_lds_dwordx4 v[164:165], off
	s_waitcnt vmcnt(8)
	s_waitcnt lgkmcnt(0)
	s_barrier
	s_setprio 1
	s_waitcnt lgkmcnt(0)
	v_mfma_f32_16x16x32_bf16 v[72:75], v[60:63], v[206:209], v[72:75]
	v_mfma_f32_16x16x32_bf16 v[64:67], v[76:79], v[206:209], v[64:67]
	v_mfma_f32_16x16x32_bf16 v[48:51], v[60:63], v[214:217], v[48:51]
	v_mfma_f32_16x16x32_bf16 v[44:47], v[76:79], v[214:217], v[44:47]
	v_mfma_f32_16x16x32_bf16 v[32:35], v[60:63], v[230:233], v[32:35]
	v_mfma_f32_16x16x32_bf16 v[28:31], v[76:79], v[230:233], v[28:31]
	v_mfma_f32_16x16x32_bf16 v[16:19], v[60:63], v[242:245], v[16:19]
	v_mfma_f32_16x16x32_bf16 v[12:15], v[76:79], v[242:245], v[12:15]
	v_mfma_f32_16x16x32_bf16 v[72:75], v[68:71], v[210:213], v[72:75]
	v_mfma_f32_16x16x32_bf16 v[64:67], v[80:83], v[210:213], v[64:67]
	v_mfma_f32_16x16x32_bf16 v[48:51], v[68:71], v[218:221], v[48:51]
	v_mfma_f32_16x16x32_bf16 v[44:47], v[80:83], v[218:221], v[44:47]
	v_mfma_f32_16x16x32_bf16 v[32:35], v[68:71], v[238:241], v[32:35]
	v_mfma_f32_16x16x32_bf16 v[28:31], v[80:83], v[238:241], v[28:31]
	v_mfma_f32_16x16x32_bf16 v[16:19], v[68:71], v[246:249], v[16:19]
	v_mfma_f32_16x16x32_bf16 v[12:15], v[80:83], v[246:249], v[12:15]
	s_setprio 0
	s_setprio 1
	v_mfma_f32_16x16x32_bf16 v[56:59], v[148:151], v[206:209], v[56:59]
	v_mfma_f32_16x16x32_bf16 v[52:55], v[156:159], v[206:209], v[52:55]
	v_mfma_f32_16x16x32_bf16 v[40:43], v[148:151], v[214:217], v[40:43]
	v_mfma_f32_16x16x32_bf16 v[36:39], v[156:159], v[214:217], v[36:39]
	v_mfma_f32_16x16x32_bf16 v[24:27], v[148:151], v[230:233], v[24:27]
	v_mfma_f32_16x16x32_bf16 v[20:23], v[156:159], v[230:233], v[20:23]
	v_mfma_f32_16x16x32_bf16 v[8:11], v[148:151], v[242:245], v[8:11]
	v_mfma_f32_16x16x32_bf16 v[4:7], v[156:159], v[242:245], v[4:7]
	v_mfma_f32_16x16x32_bf16 v[56:59], v[152:155], v[210:213], v[56:59]
	v_mfma_f32_16x16x32_bf16 v[52:55], v[160:163], v[210:213], v[52:55]
	v_mfma_f32_16x16x32_bf16 v[40:43], v[152:155], v[218:221], v[40:43]
	v_mfma_f32_16x16x32_bf16 v[36:39], v[160:163], v[218:221], v[36:39]
	v_mfma_f32_16x16x32_bf16 v[24:27], v[152:155], v[238:241], v[24:27]
	v_mfma_f32_16x16x32_bf16 v[20:23], v[160:163], v[238:241], v[20:23]
	v_mfma_f32_16x16x32_bf16 v[8:11], v[152:155], v[246:249], v[8:11]
	v_mfma_f32_16x16x32_bf16 v[4:7], v[160:163], v[246:249], v[4:7]
	s_setprio 0
	s_barrier
	s_add_u32 s26, s26, 0x100
	s_addc_u32 s27, s27, 0
	s_add_u32 s11, s11, 0x100
	s_addc_u32 s42, s42, 0
	s_cmp_ge_i32 s43, s74
	s_mov_b32 s40, s43
	s_cbranch_scc0 .LBB0_131
	s_branch .Lpeel_exit_131

; #define PG8_BAR __builtin_amdgcn_s_barrier()
; template <class Epi, class Sched>
; __device__ __forceinline__ void gemm_phase(const int tid, LAS unsigned char* lds, const bf16* Aop, const bf16* Bop, const int K_, const Sched& S, const Epi& E, const bf16* Aop1 = nullptr, const bf16* Bop1 = nullptr) {
;     ...
;         }
;         if (wr == 0) PG8_BAR;
;         E(acc, cur, wr, wc, fr, fq);
;         if (!has_next) break;
.Lpeel_exit_131:
	v_mov_b64_e32 v[248:249], v[226:227]
	v_mov_b64_e32 v[250:251], 0xff
	v_mov_b32_e32 v226, v200
	v_mov_b32_e32 v227, v203
	v_mov_b32_e32 v247, v205
	v_mov_b64_e32 v[190:191], v[176:177]
	v_mov_b64_e32 v[176:177], v[178:179]
	v_mov_b64_e32 v[178:179], v[180:181]
	s_and_b64 vcc, exec, s[28:29]
	s_cbranch_vccz .LBB0_135
	s_branch .LBB0_134

; #define PG8_GOFFS(slot_) do { _Pragma("unroll") for (int _i = 0; _i < 2; ++_i) { int R, C; stage_rc(tid * 16 + _i * 8192, R, C); _Pragma("unroll") for (int _h = 0; _h < 2; ++_h) { \
;         unsigned t_ = gtab[(slot_) * 256 + R + 128 * _h]; t_ = t_ < (unsigned)(T - 1) ? t_ : (unsigned)(T - 1); voffA[_h][_i] = (t_ * (unsigned)K + (unsigned)C) * 2u; } } } while (0)
; #define PG8_STAGE(bufoff, gbase, voff) do { _Pragma("unroll") for (int _i = 0; _i < 2; ++_i) \
;         __builtin_amdgcn_global_load_lds((const unsigned*)((const char*)(gbase) + (voff)[_i]), (LAS unsigned*)(lds + (bufoff) + ldsw + _i * 8192), 16, 0, 0); } while (0)
; #define PG8_STAGE_A1(bufoff, gbase) do { if (Epi::GATHER) PG8_STAGE(bufoff, gbase, voffA[1]); else PG8_STAGE(bufoff, (gbase) + hstep, voffA[0]); } while (0)
; #define PG8_LDA(dst, b, h) do { _Pragma("unroll") for (int m = 0; m < 4; ++m) _Pragma("unroll") for (int k = 0; k < 2; ++k) dst[m][k] = *(const LAS bf16x8*)(lds + PG8_SA(b, h) + aoff + m * 2048 + k * 1024); } while (0)
; #define PG8_WAIT_V(n) asm volatile("s_waitcnt vmcnt(" #n ")" ::: "memory")
; #define PG8_WAIT_L(n) asm volatile("s_waitcnt lgkmcnt(" #n ")" ::: "memory")
; #define PG8_BAR __builtin_amdgcn_s_barrier()
; template <class Epi, class Sched>
; __device__ __forceinline__ void gemm_phase(const int tid, LAS unsigned char* lds, const bf16* Aop, const bf16* Bop, const int K_, const Sched& S, const Epi& E, const bf16* Aop1 = nullptr, const bf16* Bop1 = nullptr) {
;     ...
;         for (int t = 0; t < nt; t += 2) {
;             const bool last = (t == nt - 2);
;             const char* a1 = cA + (size_t)(t + 1) * kstep;
;             const char* a2 = last ? nA : cA + (size_t)(t + 2) * kstep; const char* b2 = last ? nB : cB + (size_t)(t + 2) * kstep;
;             const char* a3 = a2 + kstep; const char* b3 = b2 + kstep;
;             PG8_LDB(B0, 0, 0); PG8_LDB(B1, 0, 1); PG8_SCHED; PG8_LDA(At, 0, 0); PG8_STAGE_A1(PG8_SA(1, 1), a1);
;             PG8_WAIT_V(8); PG8_WAIT_L(0); PG8_BAR; PG8_MMA(0, 0, At, B0); PG8_MMA(0, 1, At, B1); PG8_BAR; PG8_SCHED;
;             PG8_LDA(At, 0, 1); PG8_STAGE(PG8_SB(0, 0), b2, voffB); PG8_STAGE(PG8_SB(0, 1), b2 + hstep, voffB); if (Epi::GATHER && last && has_next) PG8_GOFFS((ui + 1) & 1); PG8_STAGE(PG8_SA(0, 0), a2, voffA[0]);
;             PG8_WAIT_V(8); PG8_WAIT_L(0); PG8_BAR; PG8_MMA(1, 0, At, B0); PG8_MMA(1, 1, At, B1); PG8_BAR; PG8_SCHED;
.LBB0_998:
	v_mov_b32_e32 v131, 0
	s_andn2_b64 vcc, exec, s[44:45]
	s_cbranch_vccnz .LBB0_1001
	s_add_u32 s12, s12, 0x80
	s_addc_u32 s13, s13, 0
	s_add_u32 s11, s26, 0x100
	s_addc_u32 s71, s27, 0
	s_mov_b32 s26, 0
	s_add_i32 s72, s26, 2
	s_add_u32 s73, s12, 0x80
	s_addc_u32 s27, s13, 0
	s_add_i32 s76, 0, 0x10000
	s_cmp_eq_u32 s64, s26
	s_cselect_b32 s27, s7, s27
	s_cselect_b32 s26, s6, s73
	s_cselect_b32 s75, s41, s71
	s_cselect_b32 s74, s40, s11
	s_add_i32 s73, 0, 0x14000
	v_add_u32_e32 v156, s76, v171
	v_add_u32_e32 v178, s73, v171
	ds_read_b128 v[132:135], v156
	ds_read_b128 v[148:151], v156 offset:1024
	ds_read_b128 v[152:155], v156 offset:2048
	ds_read_b128 v[156:159], v156 offset:3072
	ds_read_b128 v[160:163], v178
	ds_read_b128 v[164:167], v178 offset:1024
	ds_read_b128 v[174:177], v178 offset:2048
	ds_read_b128 v[178:181], v178 offset:3072
	v_lshl_add_u64 v[194:195], s[12:13], 0, v[144:145]
	s_add_i32 m0, s56, 0xc000
	ds_read_b128 v[182:185], v173
	ds_read_b128 v[186:189], v173 offset:1024
	ds_read_b128 v[190:193], v173 offset:2048
	ds_read_b128 v[202:205], v173 offset:3072
	ds_read_b128 v[206:209], v173 offset:4096
	ds_read_b128 v[210:213], v173 offset:5120
	ds_read_b128 v[214:217], v173 offset:6144
	ds_read_b128 v[218:221], v173 offset:7168
	global_load_lds_dwordx4 v[194:195], off
	v_lshl_add_u64 v[194:195], s[12:13], 0, v[146:147]
	s_add_i32 m0, s56, 0xe000
	s_nop 0
	global_load_lds_dwordx4 v[194:195], off
	s_waitcnt vmcnt(8)
	s_waitcnt lgkmcnt(0)
	s_barrier
	s_setprio 1
	s_waitcnt lgkmcnt(0)
	v_mfma_f32_16x16x32_bf16 v[128:131], v[132:135], v[182:185], 0
	v_mfma_f32_16x16x32_bf16 v[124:127], v[152:155], v[182:185], 0
	v_mfma_f32_16x16x32_bf16 v[112:115], v[132:135], v[190:193], 0
	v_mfma_f32_16x16x32_bf16 v[108:111], v[152:155], v[190:193], 0
	v_mfma_f32_16x16x32_bf16 v[96:99], v[132:135], v[206:209], 0
	v_mfma_f32_16x16x32_bf16 v[92:95], v[152:155], v[206:209], 0
	v_mfma_f32_16x16x32_bf16 v[80:83], v[132:135], v[214:217], 0
	v_mfma_f32_16x16x32_bf16 v[76:79], v[152:155], v[214:217], 0
	v_mfma_f32_16x16x32_bf16 v[128:131], v[148:151], v[186:189], v[128:131]
	v_mfma_f32_16x16x32_bf16 v[124:127], v[156:159], v[186:189], v[124:127]
	v_mfma_f32_16x16x32_bf16 v[112:115], v[148:151], v[202:205], v[112:115]
	v_mfma_f32_16x16x32_bf16 v[108:111], v[156:159], v[202:205], v[108:111]
	v_mfma_f32_16x16x32_bf16 v[96:99], v[148:151], v[210:213], v[96:99]
	v_mfma_f32_16x16x32_bf16 v[92:95], v[156:159], v[210:213], v[92:95]
	v_mfma_f32_16x16x32_bf16 v[80:83], v[148:151], v[218:221], v[80:83]
	v_mfma_f32_16x16x32_bf16 v[76:79], v[156:159], v[218:221], v[76:79]
	s_setprio 0
	s_setprio 1
	v_mfma_f32_16x16x32_bf16 v[120:123], v[160:163], v[182:185], 0
	v_mfma_f32_16x16x32_bf16 v[116:119], v[174:177], v[182:185], 0
	v_mfma_f32_16x16x32_bf16 v[104:107], v[160:163], v[190:193], 0
	v_mfma_f32_16x16x32_bf16 v[100:103], v[174:177], v[190:193], 0
	v_mfma_f32_16x16x32_bf16 v[88:91], v[160:163], v[206:209], 0
	v_mfma_f32_16x16x32_bf16 v[84:87], v[174:177], v[206:209], 0
	v_mfma_f32_16x16x32_bf16 v[72:75], v[160:163], v[214:217], 0
	v_mfma_f32_16x16x32_bf16 v[68:71], v[174:177], v[214:217], 0
	v_mfma_f32_16x16x32_bf16 v[120:123], v[164:167], v[186:189], v[120:123]
	v_mfma_f32_16x16x32_bf16 v[116:119], v[178:181], v[186:189], v[116:119]
	v_mfma_f32_16x16x32_bf16 v[104:107], v[164:167], v[202:205], v[104:107]
	v_mfma_f32_16x16x32_bf16 v[100:103], v[178:181], v[202:205], v[100:103]
	v_mfma_f32_16x16x32_bf16 v[88:91], v[164:167], v[210:213], v[88:91]
	v_mfma_f32_16x16x32_bf16 v[84:87], v[178:181], v[210:213], v[84:87]
	v_mfma_f32_16x16x32_bf16 v[72:75], v[164:167], v[218:221], v[72:75]
	v_mfma_f32_16x16x32_bf16 v[68:71], v[178:181], v[218:221], v[68:71]
	s_setprio 0
	s_barrier
	s_add_i32 s76, s76, s55
	v_lshl_add_u64 v[194:195], s[74:75], 0, v[136:137]
	s_mov_b32 m0, s76
	ds_read_b128 v[182:185], v173 offset:16384
	ds_read_b128 v[186:189], v173 offset:17408
	ds_read_b128 v[190:193], v173 offset:18432
	ds_read_b128 v[202:205], v173 offset:19456
	ds_read_b128 v[206:209], v173 offset:20480
	ds_read_b128 v[210:213], v173 offset:21504
	ds_read_b128 v[214:217], v173 offset:22528
	ds_read_b128 v[218:221], v173 offset:23552
	global_load_lds_dwordx4 v[194:195], off
	s_add_i32 m0, s76, 0x2000
	v_lshl_add_u64 v[196:197], s[74:75], 0, v[140:141]
	s_add_u32 s74, s74, s18
	s_addc_u32 s75, s75, s19
	s_add_i32 s73, s73, s55
	global_load_lds_dwordx4 v[196:197], off
	v_lshl_add_u64 v[198:199], s[74:75], 0, v[136:137]
	s_mov_b32 m0, s73
	v_lshl_add_u64 v[222:223], s[74:75], 0, v[140:141]
	global_load_lds_dwordx4 v[198:199], off
	s_add_i32 m0, s73, 0x2000
	v_lshl_add_u64 v[224:225], s[26:27], 0, v[0:1]
	global_load_lds_dwordx4 v[222:223], off
	s_mov_b32 m0, s56
	v_lshl_add_u64 v[230:231], s[26:27], 0, v[138:139]
	global_load_lds_dwordx4 v[224:225], off
	s_mov_b32 m0, s57
	s_nop 0
	global_load_lds_dwordx4 v[230:231], off
	s_waitcnt vmcnt(8)
	s_waitcnt lgkmcnt(0)
	s_barrier
; #define PG8_STAGE_A1(bufoff, gbase) do { if (Epi::GATHER) PG8_STAGE(bufoff, gbase, voffA[1]); else PG8_STAGE(bufoff, (gbase) + hstep, voffA[0]); } while (0)
; #define PG8_LDA(dst, b, h) do { _Pragma("unroll") for (int m = 0; m < 4; ++m) _Pragma("unroll") for (int k = 0; k < 2; ++k) dst[m][k] = *(const LAS bf16x8*)(lds + PG8_SA(b, h) + aoff + m * 2048 + k * 1024); } while (0)
; #define PG8_LDB(dst, b, h) do { _Pragma("unroll") for (int n = 0; n < 2; ++n) _Pragma("unroll") for (int k = 0; k < 2; ++k) dst[n][k] = *(const LAS bf16x8*)(lds + PG8_SB(b, h) + boff + n * 2048 + k * 1024); } while (0)
; #define PG8_MMA(ai, bj, At, Bt) do { __builtin_amdgcn_s_setprio(1); _Pragma("unroll") for (int m = 0; m < 4; ++m) _Pragma("unroll") for (int n = 0; n < 2; ++n) _Pragma("unroll") for (int k = 0; k < 2; ++k) \
;         acc[ai][bj][m][n] = __builtin_amdgcn_mfma_f32_16x16x32_bf16(Bt[n][k], At[m][k], acc[ai][bj][m][n], 0, 0, 0); __builtin_amdgcn_s_setprio(0); } while (0)
; #define PG8_WAIT_V(n) asm volatile("s_waitcnt vmcnt(" #n ")" ::: "memory")
; #define PG8_WAIT_L(n) asm volatile("s_waitcnt lgkmcnt(" #n ")" ::: "memory")
; #define PG8_BAR __builtin_amdgcn_s_barrier()
; #define PG8_SCHED __builtin_amdgcn_sched_barrier(0)
; template <class Epi, class Sched>
; __device__ __forceinline__ void gemm_phase(const int tid, LAS unsigned char* lds, const bf16* Aop, const bf16* Bop, const int K_, const Sched& S, const Epi& E, const bf16* Aop1 = nullptr, const bf16* Bop1 = nullptr) {
;     ...
;             PG8_WAIT_V(8); PG8_WAIT_L(0); PG8_BAR; PG8_MMA(1, 0, At, B0); PG8_MMA(1, 1, At, B1); PG8_BAR; PG8_SCHED;
;             PG8_LDB(B0, 1, 0); PG8_LDB(B1, 1, 1); PG8_SCHED; PG8_LDA(At, 1, 0); PG8_STAGE_A1(PG8_SA(0, 1), a2);
;             PG8_WAIT_V(8); PG8_WAIT_L(0); PG8_BAR; PG8_MMA(0, 0, At, B0); PG8_MMA(0, 1, At, B1); PG8_BAR; PG8_SCHED;
	s_setprio 1
	s_waitcnt lgkmcnt(0)
	v_mfma_f32_16x16x32_bf16 v[64:67], v[132:135], v[182:185], 0
	v_mfma_f32_16x16x32_bf16 v[60:63], v[152:155], v[182:185], 0
	v_mfma_f32_16x16x32_bf16 v[48:51], v[132:135], v[190:193], 0
	v_mfma_f32_16x16x32_bf16 v[44:47], v[152:155], v[190:193], 0
	v_mfma_f32_16x16x32_bf16 v[32:35], v[132:135], v[206:209], 0
	v_mfma_f32_16x16x32_bf16 v[28:31], v[152:155], v[206:209], 0
	v_mfma_f32_16x16x32_bf16 v[16:19], v[132:135], v[214:217], 0
	v_mfma_f32_16x16x32_bf16 v[12:15], v[152:155], v[214:217], 0
	v_mfma_f32_16x16x32_bf16 v[64:67], v[148:151], v[186:189], v[64:67]
	v_mfma_f32_16x16x32_bf16 v[60:63], v[156:159], v[186:189], v[60:63]
	v_mfma_f32_16x16x32_bf16 v[48:51], v[148:151], v[202:205], v[48:51]
	v_mfma_f32_16x16x32_bf16 v[44:47], v[156:159], v[202:205], v[44:47]
	v_mfma_f32_16x16x32_bf16 v[32:35], v[148:151], v[210:213], v[32:35]
	v_mfma_f32_16x16x32_bf16 v[28:31], v[156:159], v[210:213], v[28:31]
	v_mfma_f32_16x16x32_bf16 v[16:19], v[148:151], v[218:221], v[16:19]
	v_mfma_f32_16x16x32_bf16 v[12:15], v[156:159], v[218:221], v[12:15]
	s_setprio 0
	s_setprio 1
	v_mfma_f32_16x16x32_bf16 v[56:59], v[160:163], v[182:185], 0
	v_mfma_f32_16x16x32_bf16 v[52:55], v[174:177], v[182:185], 0
	v_mfma_f32_16x16x32_bf16 v[40:43], v[160:163], v[190:193], 0
	v_mfma_f32_16x16x32_bf16 v[36:39], v[174:177], v[190:193], 0
	v_mfma_f32_16x16x32_bf16 v[24:27], v[160:163], v[206:209], 0
	v_mfma_f32_16x16x32_bf16 v[20:23], v[174:177], v[206:209], 0
	v_mfma_f32_16x16x32_bf16 v[8:11], v[160:163], v[214:217], 0
	v_mfma_f32_16x16x32_bf16 v[4:7], v[174:177], v[214:217], 0
	v_mfma_f32_16x16x32_bf16 v[56:59], v[164:167], v[186:189], v[56:59]
	v_mfma_f32_16x16x32_bf16 v[52:55], v[178:181], v[186:189], v[52:55]
	v_mfma_f32_16x16x32_bf16 v[40:43], v[164:167], v[202:205], v[40:43]
	v_mfma_f32_16x16x32_bf16 v[36:39], v[178:181], v[202:205], v[36:39]
	v_mfma_f32_16x16x32_bf16 v[24:27], v[164:167], v[210:213], v[24:27]
	v_mfma_f32_16x16x32_bf16 v[20:23], v[178:181], v[210:213], v[20:23]
	v_mfma_f32_16x16x32_bf16 v[8:11], v[164:167], v[218:221], v[8:11]
	v_mfma_f32_16x16x32_bf16 v[4:7], v[178:181], v[218:221], v[4:7]
	s_setprio 0
	s_barrier
	s_add_i32 s73, 0, 0x18000
	s_add_i32 s74, 0, 0x1c000
	v_add_u32_e32 v156, s73, v171
	v_add_u32_e32 v178, s74, v171
	ds_read_b128 v[132:135], v156
	ds_read_b128 v[148:151], v156 offset:1024
	ds_read_b128 v[152:155], v156 offset:2048
	ds_read_b128 v[156:159], v156 offset:3072
	ds_read_b128 v[160:163], v178
	ds_read_b128 v[164:167], v178 offset:1024
	ds_read_b128 v[174:177], v178 offset:2048
	ds_read_b128 v[178:181], v178 offset:3072
	s_add_u32 s26, s26, s18
	s_addc_u32 s27, s27, s19
	s_mov_b32 m0, s58
	v_lshl_add_u64 v[232:233], s[26:27], 0, v[0:1]
	ds_read_b128 v[182:185], v173 offset:32768
	ds_read_b128 v[186:189], v173 offset:33792
	ds_read_b128 v[190:193], v173 offset:34816
	ds_read_b128 v[202:205], v173 offset:35840
	ds_read_b128 v[206:209], v173 offset:36864
	ds_read_b128 v[210:213], v173 offset:37888
	ds_read_b128 v[214:217], v173 offset:38912
	ds_read_b128 v[218:221], v173 offset:39936
	global_load_lds_dwordx4 v[232:233], off
	v_lshl_add_u64 v[232:233], s[26:27], 0, v[138:139]
	s_mov_b32 m0, s59
	s_nop 0
	global_load_lds_dwordx4 v[232:233], off
	s_waitcnt vmcnt(8)
	s_waitcnt lgkmcnt(0)
	s_barrier
	s_setprio 1
	s_waitcnt lgkmcnt(0)
	v_mfma_f32_16x16x32_bf16 v[128:131], v[132:135], v[182:185], v[128:131]
	v_mfma_f32_16x16x32_bf16 v[124:127], v[152:155], v[182:185], v[124:127]
	v_mfma_f32_16x16x32_bf16 v[112:115], v[132:135], v[190:193], v[112:115]
	v_mfma_f32_16x16x32_bf16 v[108:111], v[152:155], v[190:193], v[108:111]
	v_mfma_f32_16x16x32_bf16 v[96:99], v[132:135], v[206:209], v[96:99]
	v_mfma_f32_16x16x32_bf16 v[92:95], v[152:155], v[206:209], v[92:95]
	v_mfma_f32_16x16x32_bf16 v[80:83], v[132:135], v[214:217], v[80:83]
	v_mfma_f32_16x16x32_bf16 v[76:79], v[152:155], v[214:217], v[76:79]
	v_mfma_f32_16x16x32_bf16 v[128:131], v[148:151], v[186:189], v[128:131]
	v_mfma_f32_16x16x32_bf16 v[124:127], v[156:159], v[186:189], v[124:127]
	v_mfma_f32_16x16x32_bf16 v[112:115], v[148:151], v[202:205], v[112:115]
	v_mfma_f32_16x16x32_bf16 v[108:111], v[156:159], v[202:205], v[108:111]
	v_mfma_f32_16x16x32_bf16 v[96:99], v[148:151], v[210:213], v[96:99]
	v_mfma_f32_16x16x32_bf16 v[92:95], v[156:159], v[210:213], v[92:95]
	v_mfma_f32_16x16x32_bf16 v[80:83], v[148:151], v[218:221], v[80:83]
	v_mfma_f32_16x16x32_bf16 v[76:79], v[156:159], v[218:221], v[76:79]
	s_setprio 0
	s_setprio 1
	v_mfma_f32_16x16x32_bf16 v[120:123], v[160:163], v[182:185], v[120:123]
	v_mfma_f32_16x16x32_bf16 v[116:119], v[174:177], v[182:185], v[116:119]
	v_mfma_f32_16x16x32_bf16 v[104:107], v[160:163], v[190:193], v[104:107]
	v_mfma_f32_16x16x32_bf16 v[100:103], v[174:177], v[190:193], v[100:103]
	v_mfma_f32_16x16x32_bf16 v[88:91], v[160:163], v[206:209], v[88:91]
	v_mfma_f32_16x16x32_bf16 v[84:87], v[174:177], v[206:209], v[84:87]
	v_mfma_f32_16x16x32_bf16 v[72:75], v[160:163], v[214:217], v[72:75]
	v_mfma_f32_16x16x32_bf16 v[68:71], v[174:177], v[214:217], v[68:71]
	v_mfma_f32_16x16x32_bf16 v[120:123], v[164:167], v[186:189], v[120:123]
	v_mfma_f32_16x16x32_bf16 v[116:119], v[178:181], v[186:189], v[116:119]
	v_mfma_f32_16x16x32_bf16 v[104:107], v[164:167], v[202:205], v[104:107]
	v_mfma_f32_16x16x32_bf16 v[100:103], v[178:181], v[202:205], v[100:103]
	v_mfma_f32_16x16x32_bf16 v[88:91], v[164:167], v[210:213], v[88:91]
	v_mfma_f32_16x16x32_bf16 v[84:87], v[178:181], v[210:213], v[84:87]
	v_mfma_f32_16x16x32_bf16 v[72:75], v[164:167], v[218:221], v[72:75]
	v_mfma_f32_16x16x32_bf16 v[68:71], v[178:181], v[218:221], v[68:71]
	s_setprio 0
	s_barrier
; #define PG8_STAGE(bufoff, gbase, voff) do { _Pragma("unroll") for (int _i = 0; _i < 2; ++_i) \
;         __builtin_amdgcn_global_load_lds((const unsigned*)((const char*)(gbase) + (voff)[_i]), (LAS unsigned*)(lds + (bufoff) + ldsw + _i * 8192), 16, 0, 0); } while (0)
; #define PG8_LDA(dst, b, h) do { _Pragma("unroll") for (int m = 0; m < 4; ++m) _Pragma("unroll") for (int k = 0; k < 2; ++k) dst[m][k] = *(const LAS bf16x8*)(lds + PG8_SA(b, h) + aoff + m * 2048 + k * 1024); } while (0)
; #define PG8_MMA(ai, bj, At, Bt) do { __builtin_amdgcn_s_setprio(1); _Pragma("unroll") for (int m = 0; m < 4; ++m) _Pragma("unroll") for (int n = 0; n < 2; ++n) _Pragma("unroll") for (int k = 0; k < 2; ++k) \
;         acc[ai][bj][m][n] = __builtin_amdgcn_mfma_f32_16x16x32_bf16(Bt[n][k], At[m][k], acc[ai][bj][m][n], 0, 0, 0); __builtin_amdgcn_s_setprio(0); } while (0)
; #define PG8_WAIT_V(n) asm volatile("s_waitcnt vmcnt(" #n ")" ::: "memory")
; #define PG8_WAIT_L(n) asm volatile("s_waitcnt lgkmcnt(" #n ")" ::: "memory")
; #define PG8_BAR __builtin_amdgcn_s_barrier()
; #define PG8_SCHED __builtin_amdgcn_sched_barrier(0)
; template <class Epi, class Sched>
; __device__ __forceinline__ void gemm_phase(const int tid, LAS unsigned char* lds, const bf16* Aop, const bf16* Bop, const int K_, const Sched& S, const Epi& E, const bf16* Aop1 = nullptr, const bf16* Bop1 = nullptr) {
;     ...
;             PG8_LDA(At, 1, 1); PG8_STAGE(PG8_SB(1, 0), b3, voffB); PG8_STAGE(PG8_SB(1, 1), b3 + hstep, voffB); PG8_STAGE(PG8_SA(1, 0), a3, voffA[0]);
;             PG8_WAIT_V(8); PG8_WAIT_L(0); PG8_BAR; PG8_MMA(1, 0, At, B0); PG8_MMA(1, 1, At, B1); PG8_BAR; PG8_SCHED;
;         }
	s_add_i32 s26, s73, s55
	v_lshl_add_u64 v[194:195], v[194:195], 0, s[20:21]
	s_mov_b32 m0, s26
	ds_read_b128 v[182:185], v173 offset:49152
	ds_read_b128 v[186:189], v173 offset:50176
	ds_read_b128 v[190:193], v173 offset:51200
	ds_read_b128 v[202:205], v173 offset:52224
	ds_read_b128 v[206:209], v173 offset:53248
	ds_read_b128 v[210:213], v173 offset:54272
	ds_read_b128 v[214:217], v173 offset:55296
	ds_read_b128 v[218:221], v173 offset:56320
	global_load_lds_dwordx4 v[194:195], off
	v_lshl_add_u64 v[194:195], v[196:197], 0, s[20:21]
	s_add_i32 m0, s26, 0x2000
	s_add_i32 s26, s74, s55
	global_load_lds_dwordx4 v[194:195], off
	v_lshl_add_u64 v[194:195], v[198:199], 0, s[20:21]
	s_mov_b32 m0, s26
	s_nop 0
	global_load_lds_dwordx4 v[194:195], off
	v_lshl_add_u64 v[194:195], v[222:223], 0, s[20:21]
	s_add_i32 m0, s26, 0x2000
	s_nop 0
	global_load_lds_dwordx4 v[194:195], off
	v_lshl_add_u64 v[194:195], v[224:225], 0, s[20:21]
	s_mov_b32 m0, s60
	s_nop 0
	global_load_lds_dwordx4 v[194:195], off
	v_lshl_add_u64 v[194:195], v[230:231], 0, s[20:21]
	s_mov_b32 m0, s61
	s_nop 0
	global_load_lds_dwordx4 v[194:195], off
	s_waitcnt vmcnt(8)
	s_waitcnt lgkmcnt(0)
	s_barrier
	s_setprio 1
	s_waitcnt lgkmcnt(0)
	v_mfma_f32_16x16x32_bf16 v[64:67], v[132:135], v[182:185], v[64:67]
	v_mfma_f32_16x16x32_bf16 v[60:63], v[152:155], v[182:185], v[60:63]
	v_mfma_f32_16x16x32_bf16 v[48:51], v[132:135], v[190:193], v[48:51]
	v_mfma_f32_16x16x32_bf16 v[44:47], v[152:155], v[190:193], v[44:47]
	v_mfma_f32_16x16x32_bf16 v[32:35], v[132:135], v[206:209], v[32:35]
	v_mfma_f32_16x16x32_bf16 v[28:31], v[152:155], v[206:209], v[28:31]
	v_mfma_f32_16x16x32_bf16 v[16:19], v[132:135], v[214:217], v[16:19]
	v_mfma_f32_16x16x32_bf16 v[12:15], v[152:155], v[214:217], v[12:15]
	v_mfma_f32_16x16x32_bf16 v[64:67], v[148:151], v[186:189], v[64:67]
	v_mfma_f32_16x16x32_bf16 v[60:63], v[156:159], v[186:189], v[60:63]
	v_mfma_f32_16x16x32_bf16 v[48:51], v[148:151], v[202:205], v[48:51]
	v_mfma_f32_16x16x32_bf16 v[44:47], v[156:159], v[202:205], v[44:47]
	v_mfma_f32_16x16x32_bf16 v[32:35], v[148:151], v[210:213], v[32:35]
	v_mfma_f32_16x16x32_bf16 v[28:31], v[156:159], v[210:213], v[28:31]
	v_mfma_f32_16x16x32_bf16 v[16:19], v[148:151], v[218:221], v[16:19]
	v_mfma_f32_16x16x32_bf16 v[12:15], v[156:159], v[218:221], v[12:15]
	s_setprio 0
	s_setprio 1
	v_mfma_f32_16x16x32_bf16 v[56:59], v[160:163], v[182:185], v[56:59]
	v_mfma_f32_16x16x32_bf16 v[52:55], v[174:177], v[182:185], v[52:55]
	v_mfma_f32_16x16x32_bf16 v[40:43], v[160:163], v[190:193], v[40:43]
	v_mfma_f32_16x16x32_bf16 v[36:39], v[174:177], v[190:193], v[36:39]
	v_mfma_f32_16x16x32_bf16 v[24:27], v[160:163], v[206:209], v[24:27]
	v_mfma_f32_16x16x32_bf16 v[20:23], v[174:177], v[206:209], v[20:23]
	v_mfma_f32_16x16x32_bf16 v[8:11], v[160:163], v[214:217], v[8:11]
	v_mfma_f32_16x16x32_bf16 v[4:7], v[174:177], v[214:217], v[4:7]
	v_mfma_f32_16x16x32_bf16 v[56:59], v[164:167], v[186:189], v[56:59]
	v_mfma_f32_16x16x32_bf16 v[52:55], v[178:181], v[186:189], v[52:55]
	v_mfma_f32_16x16x32_bf16 v[40:43], v[164:167], v[202:205], v[40:43]
	v_mfma_f32_16x16x32_bf16 v[36:39], v[178:181], v[202:205], v[36:39]
	v_mfma_f32_16x16x32_bf16 v[24:27], v[164:167], v[210:213], v[24:27]
	v_mfma_f32_16x16x32_bf16 v[20:23], v[178:181], v[210:213], v[20:23]
	v_mfma_f32_16x16x32_bf16 v[8:11], v[164:167], v[218:221], v[8:11]
	v_mfma_f32_16x16x32_bf16 v[4:7], v[178:181], v[218:221], v[4:7]
	s_setprio 0
	s_barrier
	s_add_u32 s12, s12, 0x100
	s_addc_u32 s13, s13, 0
	s_add_u32 s11, s11, 0x100
	s_addc_u32 s71, s71, 0
	s_cmp_ge_i32 s72, s8
	s_mov_b32 s26, s72
	s_cbranch_scc0 .LBB0_1000
	s_branch .LBB0_1001

; #define PG8_GOFFS(slot_) do { _Pragma("unroll") for (int _i = 0; _i < 2; ++_i) { int R, C; stage_rc(tid * 16 + _i * 8192, R, C); _Pragma("unroll") for (int _h = 0; _h < 2; ++_h) { \
;         unsigned t_ = gtab[(slot_) * 256 + R + 128 * _h]; t_ = t_ < (unsigned)(T - 1) ? t_ : (unsigned)(T - 1); voffA[_h][_i] = (t_ * (unsigned)K + (unsigned)C) * 2u; } } } while (0)
; #define PG8_STAGE(bufoff, gbase, voff) do { _Pragma("unroll") for (int _i = 0; _i < 2; ++_i) \
;         __builtin_amdgcn_global_load_lds((const unsigned*)((const char*)(gbase) + (voff)[_i]), (LAS unsigned*)(lds + (bufoff) + ldsw + _i * 8192), 16, 0, 0); } while (0)
; #define PG8_STAGE_A1(bufoff, gbase) do { if (Epi::GATHER) PG8_STAGE(bufoff, gbase, voffA[1]); else PG8_STAGE(bufoff, (gbase) + hstep, voffA[0]); } while (0)
; #define PG8_LDA(dst, b, h) do { _Pragma("unroll") for (int m = 0; m < 4; ++m) _Pragma("unroll") for (int k = 0; k < 2; ++k) dst[m][k] = *(const LAS bf16x8*)(lds + PG8_SA(b, h) + aoff + m * 2048 + k * 1024); } while (0)
; #define PG8_WAIT_V(n) asm volatile("s_waitcnt vmcnt(" #n ")" ::: "memory")
; #define PG8_WAIT_L(n) asm volatile("s_waitcnt lgkmcnt(" #n ")" ::: "memory")
; #define PG8_BAR __builtin_amdgcn_s_barrier()
; template <class Epi, class Sched>
; __device__ __forceinline__ void gemm_phase(const int tid, LAS unsigned char* lds, const bf16* Aop, const bf16* Bop, const int K_, const Sched& S, const Epi& E, const bf16* Aop1 = nullptr, const bf16* Bop1 = nullptr) {
;     ...
;         for (int t = 0; t < nt; t += 2) {
;             const bool last = (t == nt - 2);
;             const char* a1 = cA + (size_t)(t + 1) * kstep;
;             const char* a2 = last ? nA : cA + (size_t)(t + 2) * kstep; const char* b2 = last ? nB : cB + (size_t)(t + 2) * kstep;
;             const char* a3 = a2 + kstep; const char* b3 = b2 + kstep;
;             PG8_LDB(B0, 0, 0); PG8_LDB(B1, 0, 1); PG8_SCHED; PG8_LDA(At, 0, 0); PG8_STAGE_A1(PG8_SA(1, 1), a1);
;             PG8_WAIT_V(8); PG8_WAIT_L(0); PG8_BAR; PG8_MMA(0, 0, At, B0); PG8_MMA(0, 1, At, B1); PG8_BAR; PG8_SCHED;
;             PG8_LDA(At, 0, 1); PG8_STAGE(PG8_SB(0, 0), b2, voffB); PG8_STAGE(PG8_SB(0, 1), b2 + hstep, voffB); if (Epi::GATHER && last && has_next) PG8_GOFFS((ui + 1) & 1); PG8_STAGE(PG8_SA(0, 0), a2, voffA[0]);
;             PG8_WAIT_V(8); PG8_WAIT_L(0); PG8_BAR; PG8_MMA(1, 0, At, B0); PG8_MMA(1, 1, At, B1); PG8_BAR; PG8_SCHED;
.LBB0_1092:
	v_mov_b32_e32 v127, 0
	s_andn2_b64 vcc, exec, s[14:15]
	s_cbranch_vccnz .LBB0_1095
	s_add_u32 s34, s34, 0x80
	s_addc_u32 s35, s35, 0
	s_add_u32 s40, s36, 0x100
	s_addc_u32 s41, s37, 0
	s_mov_b32 s36, 0
	s_add_i32 s60, s36, 2
	s_add_u32 s61, s34, 0x80
	s_addc_u32 s37, s35, 0
	s_add_i32 s66, 0, 0x10000
	s_cmp_eq_u32 s56, s36
	s_cselect_b32 s37, s19, s37
	s_cselect_b32 s36, s18, s61
	v_add_u32_e32 v144, s66, v149
	s_cselect_b32 s65, s27, s41
	s_cselect_b32 s64, s26, s40
	s_add_i32 s61, 0, 0x14000
	ds_read_b128 v[152:155], v144
	ds_read_b128 v[156:159], v144 offset:1024
	ds_read_b128 v[160:163], v144 offset:2048
	ds_read_b128 v[164:167], v144 offset:3072
	v_add_u32_e32 v144, s61, v149
	ds_read_b128 v[168:171], v144
	ds_read_b128 v[172:175], v144 offset:1024
	ds_read_b128 v[176:179], v144 offset:2048
	ds_read_b128 v[180:183], v144 offset:3072
	v_lshl_add_u64 v[144:145], s[34:35], 0, v[140:141]
	s_add_i32 m0, s50, 0xc000
	ds_read_b128 v[184:187], v151
	ds_read_b128 v[188:191], v151 offset:1024
	ds_read_b128 v[192:195], v151 offset:2048
	ds_read_b128 v[202:205], v151 offset:3072
	ds_read_b128 v[206:209], v151 offset:4096
	ds_read_b128 v[210:213], v151 offset:5120
	ds_read_b128 v[214:217], v151 offset:6144
	ds_read_b128 v[218:221], v151 offset:7168
	global_load_lds_dwordx4 v[144:145], off
	v_lshl_add_u64 v[144:145], s[34:35], 0, v[142:143]
	s_add_i32 m0, s50, 0xe000
	s_nop 0
	global_load_lds_dwordx4 v[144:145], off
	s_waitcnt vmcnt(8)
	s_waitcnt lgkmcnt(0)
	s_barrier
	s_setprio 1
	s_waitcnt lgkmcnt(0)
	v_mfma_f32_16x16x32_bf16 v[124:127], v[152:155], v[184:187], 0
	v_mfma_f32_16x16x32_bf16 v[128:131], v[160:163], v[184:187], 0
	v_mfma_f32_16x16x32_bf16 v[112:115], v[152:155], v[192:195], 0
	v_mfma_f32_16x16x32_bf16 v[108:111], v[160:163], v[192:195], 0
	v_mfma_f32_16x16x32_bf16 v[96:99], v[152:155], v[206:209], 0
	v_mfma_f32_16x16x32_bf16 v[92:95], v[160:163], v[206:209], 0
	v_mfma_f32_16x16x32_bf16 v[80:83], v[152:155], v[214:217], 0
	v_mfma_f32_16x16x32_bf16 v[76:79], v[160:163], v[214:217], 0
	v_mfma_f32_16x16x32_bf16 v[124:127], v[156:159], v[188:191], v[124:127]
	v_mfma_f32_16x16x32_bf16 v[128:131], v[164:167], v[188:191], v[128:131]
	v_mfma_f32_16x16x32_bf16 v[112:115], v[156:159], v[202:205], v[112:115]
	v_mfma_f32_16x16x32_bf16 v[108:111], v[164:167], v[202:205], v[108:111]
	v_mfma_f32_16x16x32_bf16 v[96:99], v[156:159], v[210:213], v[96:99]
	v_mfma_f32_16x16x32_bf16 v[92:95], v[164:167], v[210:213], v[92:95]
	v_mfma_f32_16x16x32_bf16 v[80:83], v[156:159], v[218:221], v[80:83]
	v_mfma_f32_16x16x32_bf16 v[76:79], v[164:167], v[218:221], v[76:79]
	s_setprio 0
	s_setprio 1
	v_mfma_f32_16x16x32_bf16 v[120:123], v[168:171], v[184:187], 0
	v_mfma_f32_16x16x32_bf16 v[116:119], v[176:179], v[184:187], 0
	v_mfma_f32_16x16x32_bf16 v[104:107], v[168:171], v[192:195], 0
	v_mfma_f32_16x16x32_bf16 v[100:103], v[176:179], v[192:195], 0
	v_mfma_f32_16x16x32_bf16 v[88:91], v[168:171], v[206:209], 0
	v_mfma_f32_16x16x32_bf16 v[84:87], v[176:179], v[206:209], 0
	v_mfma_f32_16x16x32_bf16 v[72:75], v[168:171], v[214:217], 0
	v_mfma_f32_16x16x32_bf16 v[68:71], v[176:179], v[214:217], 0
	v_mfma_f32_16x16x32_bf16 v[120:123], v[172:175], v[188:191], v[120:123]
	v_mfma_f32_16x16x32_bf16 v[116:119], v[180:183], v[188:191], v[116:119]
	v_mfma_f32_16x16x32_bf16 v[104:107], v[172:175], v[202:205], v[104:107]
	v_mfma_f32_16x16x32_bf16 v[100:103], v[180:183], v[202:205], v[100:103]
	v_mfma_f32_16x16x32_bf16 v[88:91], v[172:175], v[210:213], v[88:91]
	v_mfma_f32_16x16x32_bf16 v[84:87], v[180:183], v[210:213], v[84:87]
	v_mfma_f32_16x16x32_bf16 v[72:75], v[172:175], v[218:221], v[72:75]
	v_mfma_f32_16x16x32_bf16 v[68:71], v[180:183], v[218:221], v[68:71]
	s_setprio 0
	s_barrier
	s_add_i32 s66, s66, s49
	v_lshl_add_u64 v[144:145], s[64:65], 0, v[132:133]
	s_mov_b32 m0, s66
	ds_read_b128 v[184:187], v151 offset:16384
	ds_read_b128 v[188:191], v151 offset:17408
	ds_read_b128 v[192:195], v151 offset:18432
	ds_read_b128 v[202:205], v151 offset:19456
	ds_read_b128 v[206:209], v151 offset:20480
	ds_read_b128 v[210:213], v151 offset:21504
	ds_read_b128 v[214:217], v151 offset:22528
	ds_read_b128 v[218:221], v151 offset:23552
	global_load_lds_dwordx4 v[144:145], off
	s_add_i32 m0, s66, 0x2000
	v_lshl_add_u64 v[196:197], s[64:65], 0, v[136:137]
	s_add_u32 s64, s64, s6
	s_addc_u32 s65, s65, s7
	s_add_i32 s61, s61, s49
	global_load_lds_dwordx4 v[196:197], off
	v_lshl_add_u64 v[198:199], s[64:65], 0, v[132:133]
	s_mov_b32 m0, s61
	v_lshl_add_u64 v[222:223], s[64:65], 0, v[136:137]
	global_load_lds_dwordx4 v[198:199], off
	s_add_i32 m0, s61, 0x2000
	v_lshl_add_u64 v[224:225], s[36:37], 0, v[0:1]
	global_load_lds_dwordx4 v[222:223], off
	s_mov_b32 m0, s50
	v_lshl_add_u64 v[230:231], s[36:37], 0, v[134:135]
	global_load_lds_dwordx4 v[224:225], off
	s_mov_b32 m0, s51
	s_nop 0
	global_load_lds_dwordx4 v[230:231], off
	s_waitcnt vmcnt(8)
	s_waitcnt lgkmcnt(0)
	s_barrier
; #define PG8_STAGE_A1(bufoff, gbase) do { if (Epi::GATHER) PG8_STAGE(bufoff, gbase, voffA[1]); else PG8_STAGE(bufoff, (gbase) + hstep, voffA[0]); } while (0)
; #define PG8_LDA(dst, b, h) do { _Pragma("unroll") for (int m = 0; m < 4; ++m) _Pragma("unroll") for (int k = 0; k < 2; ++k) dst[m][k] = *(const LAS bf16x8*)(lds + PG8_SA(b, h) + aoff + m * 2048 + k * 1024); } while (0)
; #define PG8_LDB(dst, b, h) do { _Pragma("unroll") for (int n = 0; n < 2; ++n) _Pragma("unroll") for (int k = 0; k < 2; ++k) dst[n][k] = *(const LAS bf16x8*)(lds + PG8_SB(b, h) + boff + n * 2048 + k * 1024); } while (0)
; #define PG8_MMA(ai, bj, At, Bt) do { __builtin_amdgcn_s_setprio(1); _Pragma("unroll") for (int m = 0; m < 4; ++m) _Pragma("unroll") for (int n = 0; n < 2; ++n) _Pragma("unroll") for (int k = 0; k < 2; ++k) \
;         acc[ai][bj][m][n] = __builtin_amdgcn_mfma_f32_16x16x32_bf16(Bt[n][k], At[m][k], acc[ai][bj][m][n], 0, 0, 0); __builtin_amdgcn_s_setprio(0); } while (0)
; #define PG8_WAIT_V(n) asm volatile("s_waitcnt vmcnt(" #n ")" ::: "memory")
; #define PG8_WAIT_L(n) asm volatile("s_waitcnt lgkmcnt(" #n ")" ::: "memory")
; #define PG8_BAR __builtin_amdgcn_s_barrier()
; #define PG8_SCHED __builtin_amdgcn_sched_barrier(0)
; template <class Epi, class Sched>
; __device__ __forceinline__ void gemm_phase(const int tid, LAS unsigned char* lds, const bf16* Aop, const bf16* Bop, const int K_, const Sched& S, const Epi& E, const bf16* Aop1 = nullptr, const bf16* Bop1 = nullptr) {
;     ...
;             PG8_WAIT_V(8); PG8_WAIT_L(0); PG8_BAR; PG8_MMA(1, 0, At, B0); PG8_MMA(1, 1, At, B1); PG8_BAR; PG8_SCHED;
;             PG8_LDB(B0, 1, 0); PG8_LDB(B1, 1, 1); PG8_SCHED; PG8_LDA(At, 1, 0); PG8_STAGE_A1(PG8_SA(0, 1), a2);
;             PG8_WAIT_V(8); PG8_WAIT_L(0); PG8_BAR; PG8_MMA(0, 0, At, B0); PG8_MMA(0, 1, At, B1); PG8_BAR; PG8_SCHED;
	s_setprio 1
	s_waitcnt lgkmcnt(0)
	v_mfma_f32_16x16x32_bf16 v[64:67], v[152:155], v[184:187], 0
	v_mfma_f32_16x16x32_bf16 v[60:63], v[160:163], v[184:187], 0
	v_mfma_f32_16x16x32_bf16 v[48:51], v[152:155], v[192:195], 0
	v_mfma_f32_16x16x32_bf16 v[44:47], v[160:163], v[192:195], 0
	v_mfma_f32_16x16x32_bf16 v[32:35], v[152:155], v[206:209], 0
	v_mfma_f32_16x16x32_bf16 v[28:31], v[160:163], v[206:209], 0
	v_mfma_f32_16x16x32_bf16 v[16:19], v[152:155], v[214:217], 0
	v_mfma_f32_16x16x32_bf16 v[12:15], v[160:163], v[214:217], 0
	v_mfma_f32_16x16x32_bf16 v[64:67], v[156:159], v[188:191], v[64:67]
	v_mfma_f32_16x16x32_bf16 v[60:63], v[164:167], v[188:191], v[60:63]
	v_mfma_f32_16x16x32_bf16 v[48:51], v[156:159], v[202:205], v[48:51]
	v_mfma_f32_16x16x32_bf16 v[44:47], v[164:167], v[202:205], v[44:47]
	v_mfma_f32_16x16x32_bf16 v[32:35], v[156:159], v[210:213], v[32:35]
	v_mfma_f32_16x16x32_bf16 v[28:31], v[164:167], v[210:213], v[28:31]
	v_mfma_f32_16x16x32_bf16 v[16:19], v[156:159], v[218:221], v[16:19]
	v_mfma_f32_16x16x32_bf16 v[12:15], v[164:167], v[218:221], v[12:15]
	s_setprio 0
	s_setprio 1
	v_mfma_f32_16x16x32_bf16 v[56:59], v[168:171], v[184:187], 0
	v_mfma_f32_16x16x32_bf16 v[52:55], v[176:179], v[184:187], 0
	v_mfma_f32_16x16x32_bf16 v[40:43], v[168:171], v[192:195], 0
	v_mfma_f32_16x16x32_bf16 v[36:39], v[176:179], v[192:195], 0
	v_mfma_f32_16x16x32_bf16 v[24:27], v[168:171], v[206:209], 0
	v_mfma_f32_16x16x32_bf16 v[20:23], v[176:179], v[206:209], 0
	v_mfma_f32_16x16x32_bf16 v[8:11], v[168:171], v[214:217], 0
	v_mfma_f32_16x16x32_bf16 v[4:7], v[176:179], v[214:217], 0
	v_mfma_f32_16x16x32_bf16 v[56:59], v[172:175], v[188:191], v[56:59]
	v_mfma_f32_16x16x32_bf16 v[52:55], v[180:183], v[188:191], v[52:55]
	v_mfma_f32_16x16x32_bf16 v[40:43], v[172:175], v[202:205], v[40:43]
	v_mfma_f32_16x16x32_bf16 v[36:39], v[180:183], v[202:205], v[36:39]
	v_mfma_f32_16x16x32_bf16 v[24:27], v[172:175], v[210:213], v[24:27]
	v_mfma_f32_16x16x32_bf16 v[20:23], v[180:183], v[210:213], v[20:23]
	v_mfma_f32_16x16x32_bf16 v[8:11], v[172:175], v[218:221], v[8:11]
	v_mfma_f32_16x16x32_bf16 v[4:7], v[180:183], v[218:221], v[4:7]
	s_setprio 0
	s_barrier
	s_add_i32 s61, 0, 0x18000
	s_add_i32 s64, 0, 0x1c000
	v_add_u32_e32 v164, s61, v149
	v_add_u32_e32 v180, s64, v149
	ds_read_b128 v[152:155], v164
	ds_read_b128 v[156:159], v164 offset:1024
	ds_read_b128 v[160:163], v164 offset:2048
	ds_read_b128 v[164:167], v164 offset:3072
	ds_read_b128 v[168:171], v180
	ds_read_b128 v[172:175], v180 offset:1024
	ds_read_b128 v[176:179], v180 offset:2048
	ds_read_b128 v[180:183], v180 offset:3072
	s_add_u32 s36, s36, s6
	s_addc_u32 s37, s37, s7
	s_mov_b32 m0, s52
	v_lshl_add_u64 v[232:233], s[36:37], 0, v[0:1]
	ds_read_b128 v[184:187], v151 offset:32768
	ds_read_b128 v[188:191], v151 offset:33792
	ds_read_b128 v[192:195], v151 offset:34816
	ds_read_b128 v[202:205], v151 offset:35840
	ds_read_b128 v[206:209], v151 offset:36864
	ds_read_b128 v[210:213], v151 offset:37888
	ds_read_b128 v[214:217], v151 offset:38912
	ds_read_b128 v[218:221], v151 offset:39936
	global_load_lds_dwordx4 v[232:233], off
	v_lshl_add_u64 v[232:233], s[36:37], 0, v[134:135]
	s_mov_b32 m0, s53
	s_nop 0
	global_load_lds_dwordx4 v[232:233], off
	s_waitcnt vmcnt(8)
	s_waitcnt lgkmcnt(0)
	s_barrier
	s_setprio 1
	s_waitcnt lgkmcnt(0)
	v_mfma_f32_16x16x32_bf16 v[124:127], v[152:155], v[184:187], v[124:127]
	v_mfma_f32_16x16x32_bf16 v[128:131], v[160:163], v[184:187], v[128:131]
	v_mfma_f32_16x16x32_bf16 v[112:115], v[152:155], v[192:195], v[112:115]
	v_mfma_f32_16x16x32_bf16 v[108:111], v[160:163], v[192:195], v[108:111]
	v_mfma_f32_16x16x32_bf16 v[96:99], v[152:155], v[206:209], v[96:99]
	v_mfma_f32_16x16x32_bf16 v[92:95], v[160:163], v[206:209], v[92:95]
	v_mfma_f32_16x16x32_bf16 v[80:83], v[152:155], v[214:217], v[80:83]
	v_mfma_f32_16x16x32_bf16 v[76:79], v[160:163], v[214:217], v[76:79]
	v_mfma_f32_16x16x32_bf16 v[124:127], v[156:159], v[188:191], v[124:127]
	v_mfma_f32_16x16x32_bf16 v[128:131], v[164:167], v[188:191], v[128:131]
	v_mfma_f32_16x16x32_bf16 v[112:115], v[156:159], v[202:205], v[112:115]
	v_mfma_f32_16x16x32_bf16 v[108:111], v[164:167], v[202:205], v[108:111]
	v_mfma_f32_16x16x32_bf16 v[96:99], v[156:159], v[210:213], v[96:99]
	v_mfma_f32_16x16x32_bf16 v[92:95], v[164:167], v[210:213], v[92:95]
	v_mfma_f32_16x16x32_bf16 v[80:83], v[156:159], v[218:221], v[80:83]
	v_mfma_f32_16x16x32_bf16 v[76:79], v[164:167], v[218:221], v[76:79]
	s_setprio 0
	s_setprio 1
	v_mfma_f32_16x16x32_bf16 v[120:123], v[168:171], v[184:187], v[120:123]
	v_mfma_f32_16x16x32_bf16 v[116:119], v[176:179], v[184:187], v[116:119]
	v_mfma_f32_16x16x32_bf16 v[104:107], v[168:171], v[192:195], v[104:107]
	v_mfma_f32_16x16x32_bf16 v[100:103], v[176:179], v[192:195], v[100:103]
	v_mfma_f32_16x16x32_bf16 v[88:91], v[168:171], v[206:209], v[88:91]
	v_mfma_f32_16x16x32_bf16 v[84:87], v[176:179], v[206:209], v[84:87]
	v_mfma_f32_16x16x32_bf16 v[72:75], v[168:171], v[214:217], v[72:75]
	v_mfma_f32_16x16x32_bf16 v[68:71], v[176:179], v[214:217], v[68:71]
	v_mfma_f32_16x16x32_bf16 v[120:123], v[172:175], v[188:191], v[120:123]
	v_mfma_f32_16x16x32_bf16 v[116:119], v[180:183], v[188:191], v[116:119]
	v_mfma_f32_16x16x32_bf16 v[104:107], v[172:175], v[202:205], v[104:107]
	v_mfma_f32_16x16x32_bf16 v[100:103], v[180:183], v[202:205], v[100:103]
	v_mfma_f32_16x16x32_bf16 v[88:91], v[172:175], v[210:213], v[88:91]
	v_mfma_f32_16x16x32_bf16 v[84:87], v[180:183], v[210:213], v[84:87]
	v_mfma_f32_16x16x32_bf16 v[72:75], v[172:175], v[218:221], v[72:75]
	v_mfma_f32_16x16x32_bf16 v[68:71], v[180:183], v[218:221], v[68:71]
	s_setprio 0
	s_barrier
; #define PG8_STAGE(bufoff, gbase, voff) do { _Pragma("unroll") for (int _i = 0; _i < 2; ++_i) \
;         __builtin_amdgcn_global_load_lds((const unsigned*)((const char*)(gbase) + (voff)[_i]), (LAS unsigned*)(lds + (bufoff) + ldsw + _i * 8192), 16, 0, 0); } while (0)
; #define PG8_LDA(dst, b, h) do { _Pragma("unroll") for (int m = 0; m < 4; ++m) _Pragma("unroll") for (int k = 0; k < 2; ++k) dst[m][k] = *(const LAS bf16x8*)(lds + PG8_SA(b, h) + aoff + m * 2048 + k * 1024); } while (0)
; #define PG8_MMA(ai, bj, At, Bt) do { __builtin_amdgcn_s_setprio(1); _Pragma("unroll") for (int m = 0; m < 4; ++m) _Pragma("unroll") for (int n = 0; n < 2; ++n) _Pragma("unroll") for (int k = 0; k < 2; ++k) \
;         acc[ai][bj][m][n] = __builtin_amdgcn_mfma_f32_16x16x32_bf16(Bt[n][k], At[m][k], acc[ai][bj][m][n], 0, 0, 0); __builtin_amdgcn_s_setprio(0); } while (0)
; #define PG8_WAIT_V(n) asm volatile("s_waitcnt vmcnt(" #n ")" ::: "memory")
; #define PG8_WAIT_L(n) asm volatile("s_waitcnt lgkmcnt(" #n ")" ::: "memory")
; #define PG8_BAR __builtin_amdgcn_s_barrier()
; #define PG8_SCHED __builtin_amdgcn_sched_barrier(0)
; template <class Epi, class Sched>
; __device__ __forceinline__ void gemm_phase(const int tid, LAS unsigned char* lds, const bf16* Aop, const bf16* Bop, const int K_, const Sched& S, const Epi& E, const bf16* Aop1 = nullptr, const bf16* Bop1 = nullptr) {
;     ...
;             PG8_LDA(At, 1, 1); PG8_STAGE(PG8_SB(1, 0), b3, voffB); PG8_STAGE(PG8_SB(1, 1), b3 + hstep, voffB); PG8_STAGE(PG8_SA(1, 0), a3, voffA[0]);
;             PG8_WAIT_V(8); PG8_WAIT_L(0); PG8_BAR; PG8_MMA(1, 0, At, B0); PG8_MMA(1, 1, At, B1); PG8_BAR; PG8_SCHED;
;         }
	s_add_i32 s36, s61, s49
	v_lshl_add_u64 v[144:145], v[144:145], 0, s[20:21]
	s_mov_b32 m0, s36
	ds_read_b128 v[184:187], v151 offset:49152
	ds_read_b128 v[188:191], v151 offset:50176
	ds_read_b128 v[192:195], v151 offset:51200
	ds_read_b128 v[202:205], v151 offset:52224
	ds_read_b128 v[206:209], v151 offset:53248
	ds_read_b128 v[210:213], v151 offset:54272
	ds_read_b128 v[214:217], v151 offset:55296
	ds_read_b128 v[218:221], v151 offset:56320
	global_load_lds_dwordx4 v[144:145], off
	v_lshl_add_u64 v[144:145], v[196:197], 0, s[20:21]
	s_add_i32 m0, s36, 0x2000
	s_add_i32 s36, s64, s49
	global_load_lds_dwordx4 v[144:145], off
	v_lshl_add_u64 v[144:145], v[198:199], 0, s[20:21]
	s_mov_b32 m0, s36
	s_nop 0
	global_load_lds_dwordx4 v[144:145], off
	v_lshl_add_u64 v[144:145], v[222:223], 0, s[20:21]
	s_add_i32 m0, s36, 0x2000
	s_nop 0
	global_load_lds_dwordx4 v[144:145], off
	v_lshl_add_u64 v[144:145], v[224:225], 0, s[20:21]
	s_mov_b32 m0, s54
	s_nop 0
	global_load_lds_dwordx4 v[144:145], off
	v_lshl_add_u64 v[144:145], v[230:231], 0, s[20:21]
	s_mov_b32 m0, s55
	s_nop 0
	global_load_lds_dwordx4 v[144:145], off
	s_waitcnt vmcnt(8)
	s_waitcnt lgkmcnt(0)
	s_barrier
	s_setprio 1
	s_waitcnt lgkmcnt(0)
	v_mfma_f32_16x16x32_bf16 v[64:67], v[152:155], v[184:187], v[64:67]
	v_mfma_f32_16x16x32_bf16 v[60:63], v[160:163], v[184:187], v[60:63]
	v_mfma_f32_16x16x32_bf16 v[48:51], v[152:155], v[192:195], v[48:51]
	v_mfma_f32_16x16x32_bf16 v[44:47], v[160:163], v[192:195], v[44:47]
	v_mfma_f32_16x16x32_bf16 v[32:35], v[152:155], v[206:209], v[32:35]
	v_mfma_f32_16x16x32_bf16 v[28:31], v[160:163], v[206:209], v[28:31]
	v_mfma_f32_16x16x32_bf16 v[16:19], v[152:155], v[214:217], v[16:19]
	v_mfma_f32_16x16x32_bf16 v[12:15], v[160:163], v[214:217], v[12:15]
	v_mfma_f32_16x16x32_bf16 v[64:67], v[156:159], v[188:191], v[64:67]
	v_mfma_f32_16x16x32_bf16 v[60:63], v[164:167], v[188:191], v[60:63]
	v_mfma_f32_16x16x32_bf16 v[48:51], v[156:159], v[202:205], v[48:51]
	v_mfma_f32_16x16x32_bf16 v[44:47], v[164:167], v[202:205], v[44:47]
	v_mfma_f32_16x16x32_bf16 v[32:35], v[156:159], v[210:213], v[32:35]
	v_mfma_f32_16x16x32_bf16 v[28:31], v[164:167], v[210:213], v[28:31]
	v_mfma_f32_16x16x32_bf16 v[16:19], v[156:159], v[218:221], v[16:19]
	v_mfma_f32_16x16x32_bf16 v[12:15], v[164:167], v[218:221], v[12:15]
	s_setprio 0
	s_setprio 1
	v_mfma_f32_16x16x32_bf16 v[56:59], v[168:171], v[184:187], v[56:59]
	v_mfma_f32_16x16x32_bf16 v[52:55], v[176:179], v[184:187], v[52:55]
	v_mfma_f32_16x16x32_bf16 v[40:43], v[168:171], v[192:195], v[40:43]
	v_mfma_f32_16x16x32_bf16 v[36:39], v[176:179], v[192:195], v[36:39]
	v_mfma_f32_16x16x32_bf16 v[24:27], v[168:171], v[206:209], v[24:27]
	v_mfma_f32_16x16x32_bf16 v[20:23], v[176:179], v[206:209], v[20:23]
	v_mfma_f32_16x16x32_bf16 v[8:11], v[168:171], v[214:217], v[8:11]
	v_mfma_f32_16x16x32_bf16 v[4:7], v[176:179], v[214:217], v[4:7]
	v_mfma_f32_16x16x32_bf16 v[56:59], v[172:175], v[188:191], v[56:59]
	v_mfma_f32_16x16x32_bf16 v[52:55], v[180:183], v[188:191], v[52:55]
	v_mfma_f32_16x16x32_bf16 v[40:43], v[172:175], v[202:205], v[40:43]
	v_mfma_f32_16x16x32_bf16 v[36:39], v[180:183], v[202:205], v[36:39]
	v_mfma_f32_16x16x32_bf16 v[24:27], v[172:175], v[210:213], v[24:27]
	v_mfma_f32_16x16x32_bf16 v[20:23], v[180:183], v[210:213], v[20:23]
	v_mfma_f32_16x16x32_bf16 v[8:11], v[172:175], v[218:221], v[8:11]
	v_mfma_f32_16x16x32_bf16 v[4:7], v[180:183], v[218:221], v[4:7]
	s_setprio 0
	s_barrier
	s_add_u32 s34, s34, 0x100
	s_addc_u32 s35, s35, 0
	s_add_u32 s40, s40, 0x100
	s_addc_u32 s41, s41, 0
	s_cmp_ge_i32 s60, s8
	s_mov_b32 s36, s60
	s_cbranch_scc0 .LBB0_1094
	s_branch .LBB0_1095

; #define PG8_GOFFS(slot_) do { _Pragma("unroll") for (int _i = 0; _i < 2; ++_i) { int R, C; stage_rc(tid * 16 + _i * 8192, R, C); _Pragma("unroll") for (int _h = 0; _h < 2; ++_h) { \
;         unsigned t_ = gtab[(slot_) * 256 + R + 128 * _h]; t_ = t_ < (unsigned)(T - 1) ? t_ : (unsigned)(T - 1); voffA[_h][_i] = (t_ * (unsigned)K + (unsigned)C) * 2u; } } } while (0)
; #define PG8_STAGE(bufoff, gbase, voff) do { _Pragma("unroll") for (int _i = 0; _i < 2; ++_i) \
;         __builtin_amdgcn_global_load_lds((const unsigned*)((const char*)(gbase) + (voff)[_i]), (LAS unsigned*)(lds + (bufoff) + ldsw + _i * 8192), 16, 0, 0); } while (0)
; #define PG8_STAGE_A1(bufoff, gbase) do { if (Epi::GATHER) PG8_STAGE(bufoff, gbase, voffA[1]); else PG8_STAGE(bufoff, (gbase) + hstep, voffA[0]); } while (0)
; #define PG8_LDA(dst, b, h) do { _Pragma("unroll") for (int m = 0; m < 4; ++m) _Pragma("unroll") for (int k = 0; k < 2; ++k) dst[m][k] = *(const LAS bf16x8*)(lds + PG8_SA(b, h) + aoff + m * 2048 + k * 1024); } while (0)
; #define PG8_WAIT_V(n) asm volatile("s_waitcnt vmcnt(" #n ")" ::: "memory")
; #define PG8_WAIT_L(n) asm volatile("s_waitcnt lgkmcnt(" #n ")" ::: "memory")
; #define PG8_BAR __builtin_amdgcn_s_barrier()
; template <class Epi, class Sched>
; __device__ __forceinline__ void gemm_phase(const int tid, LAS unsigned char* lds, const bf16* Aop, const bf16* Bop, const int K_, const Sched& S, const Epi& E, const bf16* Aop1 = nullptr, const bf16* Bop1 = nullptr) {
;     ...
;         for (int t = 0; t < nt; t += 2) {
;             const bool last = (t == nt - 2);
;             const char* a1 = cA + (size_t)(t + 1) * kstep;
;             const char* a2 = last ? nA : cA + (size_t)(t + 2) * kstep; const char* b2 = last ? nB : cB + (size_t)(t + 2) * kstep;
;             const char* a3 = a2 + kstep; const char* b3 = b2 + kstep;
;             PG8_LDB(B0, 0, 0); PG8_LDB(B1, 0, 1); PG8_SCHED; PG8_LDA(At, 0, 0); PG8_STAGE_A1(PG8_SA(1, 1), a1);
;             PG8_WAIT_V(8); PG8_WAIT_L(0); PG8_BAR; PG8_MMA(0, 0, At, B0); PG8_MMA(0, 1, At, B1); PG8_BAR; PG8_SCHED;
;             PG8_LDA(At, 0, 1); PG8_STAGE(PG8_SB(0, 0), b2, voffB); PG8_STAGE(PG8_SB(0, 1), b2 + hstep, voffB); if (Epi::GATHER && last && has_next) PG8_GOFFS((ui + 1) & 1); PG8_STAGE(PG8_SA(0, 0), a2, voffA[0]);
;             PG8_WAIT_V(8); PG8_WAIT_L(0); PG8_BAR; PG8_MMA(1, 0, At, B0); PG8_MMA(1, 1, At, B1); PG8_BAR; PG8_SCHED;
.LBB0_1398:
	v_mov_b32_e32 v127, 0
	s_andn2_b64 vcc, exec, s[16:17]
	s_cbranch_vccnz .LBB0_1401
	s_add_u32 s34, s34, 0x80
	s_addc_u32 s35, s35, 0
	s_add_u32 s65, s36, 0x100
	s_addc_u32 s66, s37, 0
	s_mov_b32 s36, 0
	s_add_i32 s67, s36, 2
	s_add_u32 s68, s34, 0x80
	s_addc_u32 s37, s35, 0
	s_add_i32 s70, 0, 0x10000
	s_cmp_eq_u32 s58, s36
	s_cselect_b32 s37, s27, s37
	s_cselect_b32 s36, s26, s68
	v_add_u32_e32 v147, s70, v144
	s_cselect_b32 s69, s29, s66
	s_cselect_b32 s68, s28, s65
	s_add_i32 s71, 0, 0x14000
	ds_read_b128 v[148:151], v147
	ds_read_b128 v[152:155], v147 offset:1024
	ds_read_b128 v[156:159], v147 offset:2048
	ds_read_b128 v[160:163], v147 offset:3072
	v_add_u32_e32 v147, s71, v144
	ds_read_b128 v[164:167], v147
	ds_read_b128 v[168:171], v147 offset:1024
	ds_read_b128 v[172:175], v147 offset:2048
	ds_read_b128 v[176:179], v147 offset:3072
	v_lshl_add_u64 v[196:197], s[34:35], 0, v[140:141]
	s_add_i32 m0, s51, 0xc000
	ds_read_b128 v[180:183], v146
	ds_read_b128 v[184:187], v146 offset:1024
	ds_read_b128 v[188:191], v146 offset:2048
	ds_read_b128 v[192:195], v146 offset:3072
	ds_read_b128 v[202:205], v146 offset:4096
	ds_read_b128 v[206:209], v146 offset:5120
	ds_read_b128 v[210:213], v146 offset:6144
	ds_read_b128 v[214:217], v146 offset:7168
	global_load_lds_dwordx4 v[196:197], off
	v_lshl_add_u64 v[196:197], s[34:35], 0, v[142:143]
	s_add_i32 m0, s51, 0xe000
	s_nop 0
	global_load_lds_dwordx4 v[196:197], off
	s_waitcnt vmcnt(8)
	s_waitcnt lgkmcnt(0)
	s_barrier
	s_setprio 1
	s_waitcnt lgkmcnt(0)
	v_mfma_f32_16x16x32_bf16 v[124:127], v[148:151], v[180:183], 0
	v_mfma_f32_16x16x32_bf16 v[128:131], v[156:159], v[180:183], 0
	v_mfma_f32_16x16x32_bf16 v[112:115], v[148:151], v[188:191], 0
	v_mfma_f32_16x16x32_bf16 v[108:111], v[156:159], v[188:191], 0
	v_mfma_f32_16x16x32_bf16 v[96:99], v[148:151], v[202:205], 0
	v_mfma_f32_16x16x32_bf16 v[92:95], v[156:159], v[202:205], 0
	v_mfma_f32_16x16x32_bf16 v[80:83], v[148:151], v[210:213], 0
	v_mfma_f32_16x16x32_bf16 v[76:79], v[156:159], v[210:213], 0
	v_mfma_f32_16x16x32_bf16 v[124:127], v[152:155], v[184:187], v[124:127]
	v_mfma_f32_16x16x32_bf16 v[128:131], v[160:163], v[184:187], v[128:131]
	v_mfma_f32_16x16x32_bf16 v[112:115], v[152:155], v[192:195], v[112:115]
	v_mfma_f32_16x16x32_bf16 v[108:111], v[160:163], v[192:195], v[108:111]
	v_mfma_f32_16x16x32_bf16 v[96:99], v[152:155], v[206:209], v[96:99]
	v_mfma_f32_16x16x32_bf16 v[92:95], v[160:163], v[206:209], v[92:95]
	v_mfma_f32_16x16x32_bf16 v[80:83], v[152:155], v[214:217], v[80:83]
	v_mfma_f32_16x16x32_bf16 v[76:79], v[160:163], v[214:217], v[76:79]
	s_setprio 0
	s_setprio 1
	v_mfma_f32_16x16x32_bf16 v[120:123], v[164:167], v[180:183], 0
	v_mfma_f32_16x16x32_bf16 v[116:119], v[172:175], v[180:183], 0
	v_mfma_f32_16x16x32_bf16 v[104:107], v[164:167], v[188:191], 0
	v_mfma_f32_16x16x32_bf16 v[100:103], v[172:175], v[188:191], 0
	v_mfma_f32_16x16x32_bf16 v[88:91], v[164:167], v[202:205], 0
	v_mfma_f32_16x16x32_bf16 v[84:87], v[172:175], v[202:205], 0
	v_mfma_f32_16x16x32_bf16 v[72:75], v[164:167], v[210:213], 0
	v_mfma_f32_16x16x32_bf16 v[68:71], v[172:175], v[210:213], 0
	v_mfma_f32_16x16x32_bf16 v[120:123], v[168:171], v[184:187], v[120:123]
	v_mfma_f32_16x16x32_bf16 v[116:119], v[176:179], v[184:187], v[116:119]
	v_mfma_f32_16x16x32_bf16 v[104:107], v[168:171], v[192:195], v[104:107]
	v_mfma_f32_16x16x32_bf16 v[100:103], v[176:179], v[192:195], v[100:103]
	v_mfma_f32_16x16x32_bf16 v[88:91], v[168:171], v[206:209], v[88:91]
	v_mfma_f32_16x16x32_bf16 v[84:87], v[176:179], v[206:209], v[84:87]
	v_mfma_f32_16x16x32_bf16 v[72:75], v[168:171], v[214:217], v[72:75]
	v_mfma_f32_16x16x32_bf16 v[68:71], v[176:179], v[214:217], v[68:71]
	s_setprio 0
	s_barrier
	s_add_i32 s70, s70, s50
	v_lshl_add_u64 v[196:197], s[68:69], 0, v[134:135]
	s_mov_b32 m0, s70
	ds_read_b128 v[180:183], v146 offset:16384
	ds_read_b128 v[184:187], v146 offset:17408
	ds_read_b128 v[188:191], v146 offset:18432
	ds_read_b128 v[192:195], v146 offset:19456
	ds_read_b128 v[202:205], v146 offset:20480
	ds_read_b128 v[206:209], v146 offset:21504
	ds_read_b128 v[210:213], v146 offset:22528
	ds_read_b128 v[214:217], v146 offset:23552
	global_load_lds_dwordx4 v[196:197], off
	s_add_i32 m0, s70, 0x2000
	v_lshl_add_u64 v[198:199], s[68:69], 0, v[0:1]
	s_add_u32 s68, s68, s6
	s_addc_u32 s69, s69, s7
	s_add_i32 s70, s71, s50
	global_load_lds_dwordx4 v[198:199], off
	v_lshl_add_u64 v[218:219], s[68:69], 0, v[134:135]
	s_mov_b32 m0, s70
	v_lshl_add_u64 v[220:221], s[68:69], 0, v[0:1]
	global_load_lds_dwordx4 v[218:219], off
	s_add_i32 m0, s70, 0x2000
	v_lshl_add_u64 v[222:223], s[36:37], 0, v[136:137]
	global_load_lds_dwordx4 v[220:221], off
	s_mov_b32 m0, s51
	v_lshl_add_u64 v[224:225], s[36:37], 0, v[132:133]
	global_load_lds_dwordx4 v[222:223], off
	s_mov_b32 m0, s52
	s_nop 0
	global_load_lds_dwordx4 v[224:225], off
	s_waitcnt vmcnt(8)
	s_waitcnt lgkmcnt(0)
	s_barrier
; #define PG8_STAGE_A1(bufoff, gbase) do { if (Epi::GATHER) PG8_STAGE(bufoff, gbase, voffA[1]); else PG8_STAGE(bufoff, (gbase) + hstep, voffA[0]); } while (0)
; #define PG8_LDA(dst, b, h) do { _Pragma("unroll") for (int m = 0; m < 4; ++m) _Pragma("unroll") for (int k = 0; k < 2; ++k) dst[m][k] = *(const LAS bf16x8*)(lds + PG8_SA(b, h) + aoff + m * 2048 + k * 1024); } while (0)
; #define PG8_LDB(dst, b, h) do { _Pragma("unroll") for (int n = 0; n < 2; ++n) _Pragma("unroll") for (int k = 0; k < 2; ++k) dst[n][k] = *(const LAS bf16x8*)(lds + PG8_SB(b, h) + boff + n * 2048 + k * 1024); } while (0)
; #define PG8_MMA(ai, bj, At, Bt) do { __builtin_amdgcn_s_setprio(1); _Pragma("unroll") for (int m = 0; m < 4; ++m) _Pragma("unroll") for (int n = 0; n < 2; ++n) _Pragma("unroll") for (int k = 0; k < 2; ++k) \
;         acc[ai][bj][m][n] = __builtin_amdgcn_mfma_f32_16x16x32_bf16(Bt[n][k], At[m][k], acc[ai][bj][m][n], 0, 0, 0); __builtin_amdgcn_s_setprio(0); } while (0)
; #define PG8_WAIT_V(n) asm volatile("s_waitcnt vmcnt(" #n ")" ::: "memory")
; #define PG8_WAIT_L(n) asm volatile("s_waitcnt lgkmcnt(" #n ")" ::: "memory")
; #define PG8_BAR __builtin_amdgcn_s_barrier()
; #define PG8_SCHED __builtin_amdgcn_sched_barrier(0)
; template <class Epi, class Sched>
; __device__ __forceinline__ void gemm_phase(const int tid, LAS unsigned char* lds, const bf16* Aop, const bf16* Bop, const int K_, const Sched& S, const Epi& E, const bf16* Aop1 = nullptr, const bf16* Bop1 = nullptr) {
;     ...
;             PG8_WAIT_V(8); PG8_WAIT_L(0); PG8_BAR; PG8_MMA(1, 0, At, B0); PG8_MMA(1, 1, At, B1); PG8_BAR; PG8_SCHED;
;             PG8_LDB(B0, 1, 0); PG8_LDB(B1, 1, 1); PG8_SCHED; PG8_LDA(At, 1, 0); PG8_STAGE_A1(PG8_SA(0, 1), a2);
;             PG8_WAIT_V(8); PG8_WAIT_L(0); PG8_BAR; PG8_MMA(0, 0, At, B0); PG8_MMA(0, 1, At, B1); PG8_BAR; PG8_SCHED;
	s_setprio 1
	s_waitcnt lgkmcnt(0)
	v_mfma_f32_16x16x32_bf16 v[64:67], v[148:151], v[180:183], 0
	v_mfma_f32_16x16x32_bf16 v[60:63], v[156:159], v[180:183], 0
	v_mfma_f32_16x16x32_bf16 v[48:51], v[148:151], v[188:191], 0
	v_mfma_f32_16x16x32_bf16 v[44:47], v[156:159], v[188:191], 0
	v_mfma_f32_16x16x32_bf16 v[32:35], v[148:151], v[202:205], 0
	v_mfma_f32_16x16x32_bf16 v[28:31], v[156:159], v[202:205], 0
	v_mfma_f32_16x16x32_bf16 v[16:19], v[148:151], v[210:213], 0
	v_mfma_f32_16x16x32_bf16 v[12:15], v[156:159], v[210:213], 0
	v_mfma_f32_16x16x32_bf16 v[64:67], v[152:155], v[184:187], v[64:67]
	v_mfma_f32_16x16x32_bf16 v[60:63], v[160:163], v[184:187], v[60:63]
	v_mfma_f32_16x16x32_bf16 v[48:51], v[152:155], v[192:195], v[48:51]
	v_mfma_f32_16x16x32_bf16 v[44:47], v[160:163], v[192:195], v[44:47]
	v_mfma_f32_16x16x32_bf16 v[32:35], v[152:155], v[206:209], v[32:35]
	v_mfma_f32_16x16x32_bf16 v[28:31], v[160:163], v[206:209], v[28:31]
	v_mfma_f32_16x16x32_bf16 v[16:19], v[152:155], v[214:217], v[16:19]
	v_mfma_f32_16x16x32_bf16 v[12:15], v[160:163], v[214:217], v[12:15]
	s_setprio 0
	s_setprio 1
	v_mfma_f32_16x16x32_bf16 v[56:59], v[164:167], v[180:183], 0
	v_mfma_f32_16x16x32_bf16 v[52:55], v[172:175], v[180:183], 0
	v_mfma_f32_16x16x32_bf16 v[40:43], v[164:167], v[188:191], 0
	v_mfma_f32_16x16x32_bf16 v[36:39], v[172:175], v[188:191], 0
	v_mfma_f32_16x16x32_bf16 v[24:27], v[164:167], v[202:205], 0
	v_mfma_f32_16x16x32_bf16 v[20:23], v[172:175], v[202:205], 0
	v_mfma_f32_16x16x32_bf16 v[8:11], v[164:167], v[210:213], 0
	v_mfma_f32_16x16x32_bf16 v[4:7], v[172:175], v[210:213], 0
	v_mfma_f32_16x16x32_bf16 v[56:59], v[168:171], v[184:187], v[56:59]
	v_mfma_f32_16x16x32_bf16 v[52:55], v[176:179], v[184:187], v[52:55]
	v_mfma_f32_16x16x32_bf16 v[40:43], v[168:171], v[192:195], v[40:43]
	v_mfma_f32_16x16x32_bf16 v[36:39], v[176:179], v[192:195], v[36:39]
	v_mfma_f32_16x16x32_bf16 v[24:27], v[168:171], v[206:209], v[24:27]
	v_mfma_f32_16x16x32_bf16 v[20:23], v[176:179], v[206:209], v[20:23]
	v_mfma_f32_16x16x32_bf16 v[8:11], v[168:171], v[214:217], v[8:11]
	v_mfma_f32_16x16x32_bf16 v[4:7], v[176:179], v[214:217], v[4:7]
	s_setprio 0
	s_barrier
	s_add_i32 s68, 0, 0x18000
	v_add_u32_e32 v147, s68, v144
	s_add_i32 s69, 0, 0x1c000
	ds_read_b128 v[148:151], v147
	ds_read_b128 v[152:155], v147 offset:1024
	ds_read_b128 v[156:159], v147 offset:2048
	ds_read_b128 v[160:163], v147 offset:3072
	v_add_u32_e32 v147, s69, v144
	ds_read_b128 v[164:167], v147
	ds_read_b128 v[168:171], v147 offset:1024
	ds_read_b128 v[172:175], v147 offset:2048
	ds_read_b128 v[176:179], v147 offset:3072
	s_add_u32 s36, s36, s6
	s_addc_u32 s37, s37, s7
	s_mov_b32 m0, s53
	v_lshl_add_u64 v[230:231], s[36:37], 0, v[136:137]
	ds_read_b128 v[180:183], v146 offset:32768
	ds_read_b128 v[184:187], v146 offset:33792
	ds_read_b128 v[188:191], v146 offset:34816
	ds_read_b128 v[192:195], v146 offset:35840
	ds_read_b128 v[202:205], v146 offset:36864
	ds_read_b128 v[206:209], v146 offset:37888
	ds_read_b128 v[210:213], v146 offset:38912
	ds_read_b128 v[214:217], v146 offset:39936
	global_load_lds_dwordx4 v[230:231], off
	v_lshl_add_u64 v[230:231], s[36:37], 0, v[132:133]
	s_mov_b32 m0, s54
	s_nop 0
	global_load_lds_dwordx4 v[230:231], off
	s_waitcnt vmcnt(8)
	s_waitcnt lgkmcnt(0)
	s_barrier
	s_setprio 1
	s_waitcnt lgkmcnt(0)
	v_mfma_f32_16x16x32_bf16 v[124:127], v[148:151], v[180:183], v[124:127]
	v_mfma_f32_16x16x32_bf16 v[128:131], v[156:159], v[180:183], v[128:131]
	v_mfma_f32_16x16x32_bf16 v[112:115], v[148:151], v[188:191], v[112:115]
	v_mfma_f32_16x16x32_bf16 v[108:111], v[156:159], v[188:191], v[108:111]
	v_mfma_f32_16x16x32_bf16 v[96:99], v[148:151], v[202:205], v[96:99]
	v_mfma_f32_16x16x32_bf16 v[92:95], v[156:159], v[202:205], v[92:95]
	v_mfma_f32_16x16x32_bf16 v[80:83], v[148:151], v[210:213], v[80:83]
	v_mfma_f32_16x16x32_bf16 v[76:79], v[156:159], v[210:213], v[76:79]
	v_mfma_f32_16x16x32_bf16 v[124:127], v[152:155], v[184:187], v[124:127]
	v_mfma_f32_16x16x32_bf16 v[128:131], v[160:163], v[184:187], v[128:131]
	v_mfma_f32_16x16x32_bf16 v[112:115], v[152:155], v[192:195], v[112:115]
	v_mfma_f32_16x16x32_bf16 v[108:111], v[160:163], v[192:195], v[108:111]
	v_mfma_f32_16x16x32_bf16 v[96:99], v[152:155], v[206:209], v[96:99]
	v_mfma_f32_16x16x32_bf16 v[92:95], v[160:163], v[206:209], v[92:95]
	v_mfma_f32_16x16x32_bf16 v[80:83], v[152:155], v[214:217], v[80:83]
	v_mfma_f32_16x16x32_bf16 v[76:79], v[160:163], v[214:217], v[76:79]
	s_setprio 0
	s_setprio 1
	v_mfma_f32_16x16x32_bf16 v[120:123], v[164:167], v[180:183], v[120:123]
	v_mfma_f32_16x16x32_bf16 v[116:119], v[172:175], v[180:183], v[116:119]
	v_mfma_f32_16x16x32_bf16 v[104:107], v[164:167], v[188:191], v[104:107]
	v_mfma_f32_16x16x32_bf16 v[100:103], v[172:175], v[188:191], v[100:103]
	v_mfma_f32_16x16x32_bf16 v[88:91], v[164:167], v[202:205], v[88:91]
	v_mfma_f32_16x16x32_bf16 v[84:87], v[172:175], v[202:205], v[84:87]
	v_mfma_f32_16x16x32_bf16 v[72:75], v[164:167], v[210:213], v[72:75]
	v_mfma_f32_16x16x32_bf16 v[68:71], v[172:175], v[210:213], v[68:71]
	v_mfma_f32_16x16x32_bf16 v[120:123], v[168:171], v[184:187], v[120:123]
	v_mfma_f32_16x16x32_bf16 v[116:119], v[176:179], v[184:187], v[116:119]
	v_mfma_f32_16x16x32_bf16 v[104:107], v[168:171], v[192:195], v[104:107]
	v_mfma_f32_16x16x32_bf16 v[100:103], v[176:179], v[192:195], v[100:103]
	v_mfma_f32_16x16x32_bf16 v[88:91], v[168:171], v[206:209], v[88:91]
	v_mfma_f32_16x16x32_bf16 v[84:87], v[176:179], v[206:209], v[84:87]
	v_mfma_f32_16x16x32_bf16 v[72:75], v[168:171], v[214:217], v[72:75]
	v_mfma_f32_16x16x32_bf16 v[68:71], v[176:179], v[214:217], v[68:71]
	s_setprio 0
	s_barrier
; #define PG8_STAGE(bufoff, gbase, voff) do { _Pragma("unroll") for (int _i = 0; _i < 2; ++_i) \
;         __builtin_amdgcn_global_load_lds((const unsigned*)((const char*)(gbase) + (voff)[_i]), (LAS unsigned*)(lds + (bufoff) + ldsw + _i * 8192), 16, 0, 0); } while (0)
; #define PG8_LDA(dst, b, h) do { _Pragma("unroll") for (int m = 0; m < 4; ++m) _Pragma("unroll") for (int k = 0; k < 2; ++k) dst[m][k] = *(const LAS bf16x8*)(lds + PG8_SA(b, h) + aoff + m * 2048 + k * 1024); } while (0)
; #define PG8_MMA(ai, bj, At, Bt) do { __builtin_amdgcn_s_setprio(1); _Pragma("unroll") for (int m = 0; m < 4; ++m) _Pragma("unroll") for (int n = 0; n < 2; ++n) _Pragma("unroll") for (int k = 0; k < 2; ++k) \
;         acc[ai][bj][m][n] = __builtin_amdgcn_mfma_f32_16x16x32_bf16(Bt[n][k], At[m][k], acc[ai][bj][m][n], 0, 0, 0); __builtin_amdgcn_s_setprio(0); } while (0)
; #define PG8_WAIT_V(n) asm volatile("s_waitcnt vmcnt(" #n ")" ::: "memory")
; #define PG8_WAIT_L(n) asm volatile("s_waitcnt lgkmcnt(" #n ")" ::: "memory")
; #define PG8_BAR __builtin_amdgcn_s_barrier()
; #define PG8_SCHED __builtin_amdgcn_sched_barrier(0)
; template <class Epi, class Sched>
; __device__ __forceinline__ void gemm_phase(const int tid, LAS unsigned char* lds, const bf16* Aop, const bf16* Bop, const int K_, const Sched& S, const Epi& E, const bf16* Aop1 = nullptr, const bf16* Bop1 = nullptr) {
;     ...
;             PG8_LDA(At, 1, 1); PG8_STAGE(PG8_SB(1, 0), b3, voffB); PG8_STAGE(PG8_SB(1, 1), b3 + hstep, voffB); PG8_STAGE(PG8_SA(1, 0), a3, voffA[0]);
;             PG8_WAIT_V(8); PG8_WAIT_L(0); PG8_BAR; PG8_MMA(1, 0, At, B0); PG8_MMA(1, 1, At, B1); PG8_BAR; PG8_SCHED;
;         }
	s_add_i32 s36, s68, s50
	v_lshl_add_u64 v[196:197], v[196:197], 0, s[20:21]
	s_mov_b32 m0, s36
	ds_read_b128 v[180:183], v146 offset:49152
	ds_read_b128 v[184:187], v146 offset:50176
	ds_read_b128 v[188:191], v146 offset:51200
	ds_read_b128 v[192:195], v146 offset:52224
	ds_read_b128 v[202:205], v146 offset:53248
	ds_read_b128 v[206:209], v146 offset:54272
	ds_read_b128 v[210:213], v146 offset:55296
	ds_read_b128 v[214:217], v146 offset:56320
	global_load_lds_dwordx4 v[196:197], off
	v_lshl_add_u64 v[196:197], v[198:199], 0, s[20:21]
	s_add_i32 m0, s36, 0x2000
	s_add_i32 s36, s69, s50
	global_load_lds_dwordx4 v[196:197], off
	v_lshl_add_u64 v[196:197], v[218:219], 0, s[20:21]
	s_mov_b32 m0, s36
	s_nop 0
	global_load_lds_dwordx4 v[196:197], off
	v_lshl_add_u64 v[196:197], v[220:221], 0, s[20:21]
	s_add_i32 m0, s36, 0x2000
	s_nop 0
	global_load_lds_dwordx4 v[196:197], off
	v_lshl_add_u64 v[196:197], v[222:223], 0, s[20:21]
	s_mov_b32 m0, s56
	s_nop 0
	global_load_lds_dwordx4 v[196:197], off
	v_lshl_add_u64 v[196:197], v[224:225], 0, s[20:21]
	s_mov_b32 m0, s57
	s_nop 0
	global_load_lds_dwordx4 v[196:197], off
	s_waitcnt vmcnt(8)
	s_waitcnt lgkmcnt(0)
	s_barrier
	s_setprio 1
	s_waitcnt lgkmcnt(0)
	v_mfma_f32_16x16x32_bf16 v[64:67], v[148:151], v[180:183], v[64:67]
	v_mfma_f32_16x16x32_bf16 v[60:63], v[156:159], v[180:183], v[60:63]
	v_mfma_f32_16x16x32_bf16 v[48:51], v[148:151], v[188:191], v[48:51]
	v_mfma_f32_16x16x32_bf16 v[44:47], v[156:159], v[188:191], v[44:47]
	v_mfma_f32_16x16x32_bf16 v[32:35], v[148:151], v[202:205], v[32:35]
	v_mfma_f32_16x16x32_bf16 v[28:31], v[156:159], v[202:205], v[28:31]
	v_mfma_f32_16x16x32_bf16 v[16:19], v[148:151], v[210:213], v[16:19]
	v_mfma_f32_16x16x32_bf16 v[12:15], v[156:159], v[210:213], v[12:15]
	v_mfma_f32_16x16x32_bf16 v[64:67], v[152:155], v[184:187], v[64:67]
	v_mfma_f32_16x16x32_bf16 v[60:63], v[160:163], v[184:187], v[60:63]
	v_mfma_f32_16x16x32_bf16 v[48:51], v[152:155], v[192:195], v[48:51]
	v_mfma_f32_16x16x32_bf16 v[44:47], v[160:163], v[192:195], v[44:47]
	v_mfma_f32_16x16x32_bf16 v[32:35], v[152:155], v[206:209], v[32:35]
	v_mfma_f32_16x16x32_bf16 v[28:31], v[160:163], v[206:209], v[28:31]
	v_mfma_f32_16x16x32_bf16 v[16:19], v[152:155], v[214:217], v[16:19]
	v_mfma_f32_16x16x32_bf16 v[12:15], v[160:163], v[214:217], v[12:15]
	s_setprio 0
	s_setprio 1
	v_mfma_f32_16x16x32_bf16 v[56:59], v[164:167], v[180:183], v[56:59]
	v_mfma_f32_16x16x32_bf16 v[52:55], v[172:175], v[180:183], v[52:55]
	v_mfma_f32_16x16x32_bf16 v[40:43], v[164:167], v[188:191], v[40:43]
	v_mfma_f32_16x16x32_bf16 v[36:39], v[172:175], v[188:191], v[36:39]
	v_mfma_f32_16x16x32_bf16 v[24:27], v[164:167], v[202:205], v[24:27]
	v_mfma_f32_16x16x32_bf16 v[20:23], v[172:175], v[202:205], v[20:23]
	v_mfma_f32_16x16x32_bf16 v[8:11], v[164:167], v[210:213], v[8:11]
	v_mfma_f32_16x16x32_bf16 v[4:7], v[172:175], v[210:213], v[4:7]
	v_mfma_f32_16x16x32_bf16 v[56:59], v[168:171], v[184:187], v[56:59]
	v_mfma_f32_16x16x32_bf16 v[52:55], v[176:179], v[184:187], v[52:55]
	v_mfma_f32_16x16x32_bf16 v[40:43], v[168:171], v[192:195], v[40:43]
	v_mfma_f32_16x16x32_bf16 v[36:39], v[176:179], v[192:195], v[36:39]
	v_mfma_f32_16x16x32_bf16 v[24:27], v[168:171], v[206:209], v[24:27]
	v_mfma_f32_16x16x32_bf16 v[20:23], v[176:179], v[206:209], v[20:23]
	v_mfma_f32_16x16x32_bf16 v[8:11], v[168:171], v[214:217], v[8:11]
	v_mfma_f32_16x16x32_bf16 v[4:7], v[176:179], v[214:217], v[4:7]
	s_setprio 0
	s_barrier
	s_add_u32 s34, s34, 0x100
	s_addc_u32 s35, s35, 0
	s_add_u32 s65, s65, 0x100
	s_addc_u32 s66, s66, 0
	s_cmp_ge_i32 s67, s55
	s_mov_b32 s36, s67
	s_cbranch_scc0 .LBB0_1400
	s_branch .LBB0_1401

; #define PG8_GOFFS(slot_) do { _Pragma("unroll") for (int _i = 0; _i < 2; ++_i) { int R, C; stage_rc(tid * 16 + _i * 8192, R, C); _Pragma("unroll") for (int _h = 0; _h < 2; ++_h) { \
;         unsigned t_ = gtab[(slot_) * 256 + R + 128 * _h]; t_ = t_ < (unsigned)(T - 1) ? t_ : (unsigned)(T - 1); voffA[_h][_i] = (t_ * (unsigned)K + (unsigned)C) * 2u; } } } while (0)
; #define PG8_STAGE(bufoff, gbase, voff) do { _Pragma("unroll") for (int _i = 0; _i < 2; ++_i) \
;         __builtin_amdgcn_global_load_lds((const unsigned*)((const char*)(gbase) + (voff)[_i]), (LAS unsigned*)(lds + (bufoff) + ldsw + _i * 8192), 16, 0, 0); } while (0)
; #define PG8_STAGE_A1(bufoff, gbase) do { if (Epi::GATHER) PG8_STAGE(bufoff, gbase, voffA[1]); else PG8_STAGE(bufoff, (gbase) + hstep, voffA[0]); } while (0)
; #define PG8_LDA(dst, b, h) do { _Pragma("unroll") for (int m = 0; m < 4; ++m) _Pragma("unroll") for (int k = 0; k < 2; ++k) dst[m][k] = *(const LAS bf16x8*)(lds + PG8_SA(b, h) + aoff + m * 2048 + k * 1024); } while (0)
; #define PG8_WAIT_V(n) asm volatile("s_waitcnt vmcnt(" #n ")" ::: "memory")
; #define PG8_WAIT_L(n) asm volatile("s_waitcnt lgkmcnt(" #n ")" ::: "memory")
; #define PG8_BAR __builtin_amdgcn_s_barrier()
; template <class Epi, class Sched>
; __device__ __forceinline__ void gemm_phase(const int tid, LAS unsigned char* lds, const bf16* Aop, const bf16* Bop, const int K_, const Sched& S, const Epi& E, const bf16* Aop1 = nullptr, const bf16* Bop1 = nullptr) {
;     ...
;         for (int t = 0; t < nt; t += 2) {
;             const bool last = (t == nt - 2);
;             const char* a1 = cA + (size_t)(t + 1) * kstep;
;             const char* a2 = last ? nA : cA + (size_t)(t + 2) * kstep; const char* b2 = last ? nB : cB + (size_t)(t + 2) * kstep;
;             const char* a3 = a2 + kstep; const char* b3 = b2 + kstep;
;             PG8_LDB(B0, 0, 0); PG8_LDB(B1, 0, 1); PG8_SCHED; PG8_LDA(At, 0, 0); PG8_STAGE_A1(PG8_SA(1, 1), a1);
;             PG8_WAIT_V(8); PG8_WAIT_L(0); PG8_BAR; PG8_MMA(0, 0, At, B0); PG8_MMA(0, 1, At, B1); PG8_BAR; PG8_SCHED;
;             PG8_LDA(At, 0, 1); PG8_STAGE(PG8_SB(0, 0), b2, voffB); PG8_STAGE(PG8_SB(0, 1), b2 + hstep, voffB); if (Epi::GATHER && last && has_next) PG8_GOFFS((ui + 1) & 1); PG8_STAGE(PG8_SA(0, 0), a2, voffA[0]);
;             PG8_WAIT_V(8); PG8_WAIT_L(0); PG8_BAR; PG8_MMA(1, 0, At, B0); PG8_MMA(1, 1, At, B1); PG8_BAR; PG8_SCHED;
.LBB0_1418:
	v_mov_b32_e32 v127, 0
	s_andn2_b64 vcc, exec, s[16:17]
	s_cbranch_vccnz .LBB0_1421
	s_add_u32 s34, s34, 0x80
	s_addc_u32 s35, s35, 0
	s_add_u32 s15, s36, 0x100
	s_addc_u32 s67, s37, 0
	s_mov_b32 s36, 0
	s_add_i32 s68, s36, 2
	s_add_u32 s69, s34, 0x80
	s_addc_u32 s37, s35, 0
	s_add_i32 s72, 0, 0x10000
	s_cmp_eq_u32 s61, s36
	s_cselect_b32 s37, s27, s37
	s_cselect_b32 s36, s26, s69
	s_cselect_b32 s71, s29, s67
	s_cselect_b32 s70, s28, s15
	s_add_i32 s69, 0, 0x14000
	v_add_u32_e32 v158, s72, v3
	v_add_u32_e32 v174, s69, v3
	ds_read_b128 v[146:149], v158
	ds_read_b128 v[150:153], v158 offset:1024
	ds_read_b128 v[154:157], v158 offset:2048
	ds_read_b128 v[158:161], v158 offset:3072
	ds_read_b128 v[162:165], v174
	ds_read_b128 v[166:169], v174 offset:1024
	ds_read_b128 v[170:173], v174 offset:2048
	ds_read_b128 v[174:177], v174 offset:3072
	v_lshl_add_u64 v[194:195], s[34:35], 0, v[140:141]
	s_add_i32 m0, s53, 0xc000
	ds_read_b128 v[178:181], v144
	ds_read_b128 v[182:185], v144 offset:1024
	ds_read_b128 v[186:189], v144 offset:2048
	ds_read_b128 v[190:193], v144 offset:3072
	ds_read_b128 v[202:205], v144 offset:4096
	ds_read_b128 v[206:209], v144 offset:5120
	ds_read_b128 v[210:213], v144 offset:6144
	ds_read_b128 v[214:217], v144 offset:7168
	global_load_lds_dwordx4 v[194:195], off
	v_lshl_add_u64 v[194:195], s[34:35], 0, v[142:143]
	s_add_i32 m0, s53, 0xe000
	s_nop 0
	global_load_lds_dwordx4 v[194:195], off
	s_waitcnt vmcnt(8)
	s_waitcnt lgkmcnt(0)
	s_barrier
	s_setprio 1
	s_waitcnt lgkmcnt(0)
	v_mfma_f32_16x16x32_bf16 v[124:127], v[146:149], v[178:181], 0
	v_mfma_f32_16x16x32_bf16 v[128:131], v[154:157], v[178:181], 0
	v_mfma_f32_16x16x32_bf16 v[112:115], v[146:149], v[186:189], 0
	v_mfma_f32_16x16x32_bf16 v[108:111], v[154:157], v[186:189], 0
	v_mfma_f32_16x16x32_bf16 v[96:99], v[146:149], v[202:205], 0
	v_mfma_f32_16x16x32_bf16 v[92:95], v[154:157], v[202:205], 0
	v_mfma_f32_16x16x32_bf16 v[80:83], v[146:149], v[210:213], 0
	v_mfma_f32_16x16x32_bf16 v[76:79], v[154:157], v[210:213], 0
	v_mfma_f32_16x16x32_bf16 v[124:127], v[150:153], v[182:185], v[124:127]
	v_mfma_f32_16x16x32_bf16 v[128:131], v[158:161], v[182:185], v[128:131]
	v_mfma_f32_16x16x32_bf16 v[112:115], v[150:153], v[190:193], v[112:115]
	v_mfma_f32_16x16x32_bf16 v[108:111], v[158:161], v[190:193], v[108:111]
	v_mfma_f32_16x16x32_bf16 v[96:99], v[150:153], v[206:209], v[96:99]
	v_mfma_f32_16x16x32_bf16 v[92:95], v[158:161], v[206:209], v[92:95]
	v_mfma_f32_16x16x32_bf16 v[80:83], v[150:153], v[214:217], v[80:83]
	v_mfma_f32_16x16x32_bf16 v[76:79], v[158:161], v[214:217], v[76:79]
	s_setprio 0
	s_setprio 1
	v_mfma_f32_16x16x32_bf16 v[120:123], v[162:165], v[178:181], 0
	v_mfma_f32_16x16x32_bf16 v[116:119], v[170:173], v[178:181], 0
	v_mfma_f32_16x16x32_bf16 v[104:107], v[162:165], v[186:189], 0
	v_mfma_f32_16x16x32_bf16 v[100:103], v[170:173], v[186:189], 0
	v_mfma_f32_16x16x32_bf16 v[88:91], v[162:165], v[202:205], 0
	v_mfma_f32_16x16x32_bf16 v[84:87], v[170:173], v[202:205], 0
	v_mfma_f32_16x16x32_bf16 v[72:75], v[162:165], v[210:213], 0
	v_mfma_f32_16x16x32_bf16 v[68:71], v[170:173], v[210:213], 0
	v_mfma_f32_16x16x32_bf16 v[120:123], v[166:169], v[182:185], v[120:123]
	v_mfma_f32_16x16x32_bf16 v[116:119], v[174:177], v[182:185], v[116:119]
	v_mfma_f32_16x16x32_bf16 v[104:107], v[166:169], v[190:193], v[104:107]
	v_mfma_f32_16x16x32_bf16 v[100:103], v[174:177], v[190:193], v[100:103]
	v_mfma_f32_16x16x32_bf16 v[88:91], v[166:169], v[206:209], v[88:91]
	v_mfma_f32_16x16x32_bf16 v[84:87], v[174:177], v[206:209], v[84:87]
	v_mfma_f32_16x16x32_bf16 v[72:75], v[166:169], v[214:217], v[72:75]
	v_mfma_f32_16x16x32_bf16 v[68:71], v[174:177], v[214:217], v[68:71]
	s_setprio 0
	s_barrier
	s_add_i32 s72, s72, s52
	v_lshl_add_u64 v[194:195], s[70:71], 0, v[134:135]
	s_mov_b32 m0, s72
	ds_read_b128 v[178:181], v144 offset:16384
	ds_read_b128 v[182:185], v144 offset:17408
	ds_read_b128 v[186:189], v144 offset:18432
	ds_read_b128 v[190:193], v144 offset:19456
	ds_read_b128 v[202:205], v144 offset:20480
	ds_read_b128 v[206:209], v144 offset:21504
	ds_read_b128 v[210:213], v144 offset:22528
	ds_read_b128 v[214:217], v144 offset:23552
	global_load_lds_dwordx4 v[194:195], off
	s_add_i32 m0, s72, 0x2000
	v_lshl_add_u64 v[196:197], s[70:71], 0, v[0:1]
	s_add_u32 s70, s70, s6
	s_addc_u32 s71, s71, s7
	s_add_i32 s69, s69, s52
	global_load_lds_dwordx4 v[196:197], off
	v_lshl_add_u64 v[198:199], s[70:71], 0, v[134:135]
	s_mov_b32 m0, s69
	v_lshl_add_u64 v[218:219], s[70:71], 0, v[0:1]
	global_load_lds_dwordx4 v[198:199], off
	s_add_i32 m0, s69, 0x2000
	v_lshl_add_u64 v[220:221], s[36:37], 0, v[136:137]
	global_load_lds_dwordx4 v[218:219], off
	s_mov_b32 m0, s53
	v_lshl_add_u64 v[222:223], s[36:37], 0, v[132:133]
	global_load_lds_dwordx4 v[220:221], off
	s_mov_b32 m0, s54
	s_nop 0
	global_load_lds_dwordx4 v[222:223], off
	s_waitcnt vmcnt(8)
	s_waitcnt lgkmcnt(0)
	s_barrier
; #define PG8_STAGE_A1(bufoff, gbase) do { if (Epi::GATHER) PG8_STAGE(bufoff, gbase, voffA[1]); else PG8_STAGE(bufoff, (gbase) + hstep, voffA[0]); } while (0)
; #define PG8_LDA(dst, b, h) do { _Pragma("unroll") for (int m = 0; m < 4; ++m) _Pragma("unroll") for (int k = 0; k < 2; ++k) dst[m][k] = *(const LAS bf16x8*)(lds + PG8_SA(b, h) + aoff + m * 2048 + k * 1024); } while (0)
; #define PG8_LDB(dst, b, h) do { _Pragma("unroll") for (int n = 0; n < 2; ++n) _Pragma("unroll") for (int k = 0; k < 2; ++k) dst[n][k] = *(const LAS bf16x8*)(lds + PG8_SB(b, h) + boff + n * 2048 + k * 1024); } while (0)
; #define PG8_MMA(ai, bj, At, Bt) do { __builtin_amdgcn_s_setprio(1); _Pragma("unroll") for (int m = 0; m < 4; ++m) _Pragma("unroll") for (int n = 0; n < 2; ++n) _Pragma("unroll") for (int k = 0; k < 2; ++k) \
;         acc[ai][bj][m][n] = __builtin_amdgcn_mfma_f32_16x16x32_bf16(Bt[n][k], At[m][k], acc[ai][bj][m][n], 0, 0, 0); __builtin_amdgcn_s_setprio(0); } while (0)
; #define PG8_WAIT_V(n) asm volatile("s_waitcnt vmcnt(" #n ")" ::: "memory")
; #define PG8_WAIT_L(n) asm volatile("s_waitcnt lgkmcnt(" #n ")" ::: "memory")
; #define PG8_BAR __builtin_amdgcn_s_barrier()
; #define PG8_SCHED __builtin_amdgcn_sched_barrier(0)
; template <class Epi, class Sched>
; __device__ __forceinline__ void gemm_phase(const int tid, LAS unsigned char* lds, const bf16* Aop, const bf16* Bop, const int K_, const Sched& S, const Epi& E, const bf16* Aop1 = nullptr, const bf16* Bop1 = nullptr) {
;     ...
;             PG8_WAIT_V(8); PG8_WAIT_L(0); PG8_BAR; PG8_MMA(1, 0, At, B0); PG8_MMA(1, 1, At, B1); PG8_BAR; PG8_SCHED;
;             PG8_LDB(B0, 1, 0); PG8_LDB(B1, 1, 1); PG8_SCHED; PG8_LDA(At, 1, 0); PG8_STAGE_A1(PG8_SA(0, 1), a2);
;             PG8_WAIT_V(8); PG8_WAIT_L(0); PG8_BAR; PG8_MMA(0, 0, At, B0); PG8_MMA(0, 1, At, B1); PG8_BAR; PG8_SCHED;
	s_setprio 1
	s_waitcnt lgkmcnt(0)
	v_mfma_f32_16x16x32_bf16 v[64:67], v[146:149], v[178:181], 0
	v_mfma_f32_16x16x32_bf16 v[60:63], v[154:157], v[178:181], 0
	v_mfma_f32_16x16x32_bf16 v[48:51], v[146:149], v[186:189], 0
	v_mfma_f32_16x16x32_bf16 v[44:47], v[154:157], v[186:189], 0
	v_mfma_f32_16x16x32_bf16 v[32:35], v[146:149], v[202:205], 0
	v_mfma_f32_16x16x32_bf16 v[28:31], v[154:157], v[202:205], 0
	v_mfma_f32_16x16x32_bf16 v[16:19], v[146:149], v[210:213], 0
	v_mfma_f32_16x16x32_bf16 v[12:15], v[154:157], v[210:213], 0
	v_mfma_f32_16x16x32_bf16 v[64:67], v[150:153], v[182:185], v[64:67]
	v_mfma_f32_16x16x32_bf16 v[60:63], v[158:161], v[182:185], v[60:63]
	v_mfma_f32_16x16x32_bf16 v[48:51], v[150:153], v[190:193], v[48:51]
	v_mfma_f32_16x16x32_bf16 v[44:47], v[158:161], v[190:193], v[44:47]
	v_mfma_f32_16x16x32_bf16 v[32:35], v[150:153], v[206:209], v[32:35]
	v_mfma_f32_16x16x32_bf16 v[28:31], v[158:161], v[206:209], v[28:31]
	v_mfma_f32_16x16x32_bf16 v[16:19], v[150:153], v[214:217], v[16:19]
	v_mfma_f32_16x16x32_bf16 v[12:15], v[158:161], v[214:217], v[12:15]
	s_setprio 0
	s_setprio 1
	v_mfma_f32_16x16x32_bf16 v[56:59], v[162:165], v[178:181], 0
	v_mfma_f32_16x16x32_bf16 v[52:55], v[170:173], v[178:181], 0
	v_mfma_f32_16x16x32_bf16 v[40:43], v[162:165], v[186:189], 0
	v_mfma_f32_16x16x32_bf16 v[36:39], v[170:173], v[186:189], 0
	v_mfma_f32_16x16x32_bf16 v[24:27], v[162:165], v[202:205], 0
	v_mfma_f32_16x16x32_bf16 v[20:23], v[170:173], v[202:205], 0
	v_mfma_f32_16x16x32_bf16 v[8:11], v[162:165], v[210:213], 0
	v_mfma_f32_16x16x32_bf16 v[4:7], v[170:173], v[210:213], 0
	v_mfma_f32_16x16x32_bf16 v[56:59], v[166:169], v[182:185], v[56:59]
	v_mfma_f32_16x16x32_bf16 v[52:55], v[174:177], v[182:185], v[52:55]
	v_mfma_f32_16x16x32_bf16 v[40:43], v[166:169], v[190:193], v[40:43]
	v_mfma_f32_16x16x32_bf16 v[36:39], v[174:177], v[190:193], v[36:39]
	v_mfma_f32_16x16x32_bf16 v[24:27], v[166:169], v[206:209], v[24:27]
	v_mfma_f32_16x16x32_bf16 v[20:23], v[174:177], v[206:209], v[20:23]
	v_mfma_f32_16x16x32_bf16 v[8:11], v[166:169], v[214:217], v[8:11]
	v_mfma_f32_16x16x32_bf16 v[4:7], v[174:177], v[214:217], v[4:7]
	s_setprio 0
	s_barrier
	s_add_i32 s69, 0, 0x18000
	s_add_i32 s70, 0, 0x1c000
	v_add_u32_e32 v158, s69, v3
	v_add_u32_e32 v174, s70, v3
	ds_read_b128 v[146:149], v158
	ds_read_b128 v[150:153], v158 offset:1024
	ds_read_b128 v[154:157], v158 offset:2048
	ds_read_b128 v[158:161], v158 offset:3072
	ds_read_b128 v[162:165], v174
	ds_read_b128 v[166:169], v174 offset:1024
	ds_read_b128 v[170:173], v174 offset:2048
	ds_read_b128 v[174:177], v174 offset:3072
	s_add_u32 s36, s36, s6
	s_addc_u32 s37, s37, s7
	s_mov_b32 m0, s55
	v_lshl_add_u64 v[224:225], s[36:37], 0, v[136:137]
	ds_read_b128 v[178:181], v144 offset:32768
	ds_read_b128 v[182:185], v144 offset:33792
	ds_read_b128 v[186:189], v144 offset:34816
	ds_read_b128 v[190:193], v144 offset:35840
	ds_read_b128 v[202:205], v144 offset:36864
	ds_read_b128 v[206:209], v144 offset:37888
	ds_read_b128 v[210:213], v144 offset:38912
	ds_read_b128 v[214:217], v144 offset:39936
	global_load_lds_dwordx4 v[224:225], off
	v_lshl_add_u64 v[224:225], s[36:37], 0, v[132:133]
	s_mov_b32 m0, s56
	s_nop 0
	global_load_lds_dwordx4 v[224:225], off
	s_waitcnt vmcnt(8)
	s_waitcnt lgkmcnt(0)
	s_barrier
	s_setprio 1
	s_waitcnt lgkmcnt(0)
	v_mfma_f32_16x16x32_bf16 v[124:127], v[146:149], v[178:181], v[124:127]
	v_mfma_f32_16x16x32_bf16 v[128:131], v[154:157], v[178:181], v[128:131]
	v_mfma_f32_16x16x32_bf16 v[112:115], v[146:149], v[186:189], v[112:115]
	v_mfma_f32_16x16x32_bf16 v[108:111], v[154:157], v[186:189], v[108:111]
	v_mfma_f32_16x16x32_bf16 v[96:99], v[146:149], v[202:205], v[96:99]
	v_mfma_f32_16x16x32_bf16 v[92:95], v[154:157], v[202:205], v[92:95]
	v_mfma_f32_16x16x32_bf16 v[80:83], v[146:149], v[210:213], v[80:83]
	v_mfma_f32_16x16x32_bf16 v[76:79], v[154:157], v[210:213], v[76:79]
	v_mfma_f32_16x16x32_bf16 v[124:127], v[150:153], v[182:185], v[124:127]
	v_mfma_f32_16x16x32_bf16 v[128:131], v[158:161], v[182:185], v[128:131]
	v_mfma_f32_16x16x32_bf16 v[112:115], v[150:153], v[190:193], v[112:115]
	v_mfma_f32_16x16x32_bf16 v[108:111], v[158:161], v[190:193], v[108:111]
	v_mfma_f32_16x16x32_bf16 v[96:99], v[150:153], v[206:209], v[96:99]
	v_mfma_f32_16x16x32_bf16 v[92:95], v[158:161], v[206:209], v[92:95]
	v_mfma_f32_16x16x32_bf16 v[80:83], v[150:153], v[214:217], v[80:83]
	v_mfma_f32_16x16x32_bf16 v[76:79], v[158:161], v[214:217], v[76:79]
	s_setprio 0
	s_setprio 1
	v_mfma_f32_16x16x32_bf16 v[120:123], v[162:165], v[178:181], v[120:123]
	v_mfma_f32_16x16x32_bf16 v[116:119], v[170:173], v[178:181], v[116:119]
	v_mfma_f32_16x16x32_bf16 v[104:107], v[162:165], v[186:189], v[104:107]
	v_mfma_f32_16x16x32_bf16 v[100:103], v[170:173], v[186:189], v[100:103]
	v_mfma_f32_16x16x32_bf16 v[88:91], v[162:165], v[202:205], v[88:91]
	v_mfma_f32_16x16x32_bf16 v[84:87], v[170:173], v[202:205], v[84:87]
	v_mfma_f32_16x16x32_bf16 v[72:75], v[162:165], v[210:213], v[72:75]
	v_mfma_f32_16x16x32_bf16 v[68:71], v[170:173], v[210:213], v[68:71]
	v_mfma_f32_16x16x32_bf16 v[120:123], v[166:169], v[182:185], v[120:123]
	v_mfma_f32_16x16x32_bf16 v[116:119], v[174:177], v[182:185], v[116:119]
	v_mfma_f32_16x16x32_bf16 v[104:107], v[166:169], v[190:193], v[104:107]
	v_mfma_f32_16x16x32_bf16 v[100:103], v[174:177], v[190:193], v[100:103]
	v_mfma_f32_16x16x32_bf16 v[88:91], v[166:169], v[206:209], v[88:91]
	v_mfma_f32_16x16x32_bf16 v[84:87], v[174:177], v[206:209], v[84:87]
	v_mfma_f32_16x16x32_bf16 v[72:75], v[166:169], v[214:217], v[72:75]
	v_mfma_f32_16x16x32_bf16 v[68:71], v[174:177], v[214:217], v[68:71]
	s_setprio 0
	s_barrier
; #define PG8_STAGE(bufoff, gbase, voff) do { _Pragma("unroll") for (int _i = 0; _i < 2; ++_i) \
;         __builtin_amdgcn_global_load_lds((const unsigned*)((const char*)(gbase) + (voff)[_i]), (LAS unsigned*)(lds + (bufoff) + ldsw + _i * 8192), 16, 0, 0); } while (0)
; #define PG8_LDA(dst, b, h) do { _Pragma("unroll") for (int m = 0; m < 4; ++m) _Pragma("unroll") for (int k = 0; k < 2; ++k) dst[m][k] = *(const LAS bf16x8*)(lds + PG8_SA(b, h) + aoff + m * 2048 + k * 1024); } while (0)
; #define PG8_MMA(ai, bj, At, Bt) do { __builtin_amdgcn_s_setprio(1); _Pragma("unroll") for (int m = 0; m < 4; ++m) _Pragma("unroll") for (int n = 0; n < 2; ++n) _Pragma("unroll") for (int k = 0; k < 2; ++k) \
;         acc[ai][bj][m][n] = __builtin_amdgcn_mfma_f32_16x16x32_bf16(Bt[n][k], At[m][k], acc[ai][bj][m][n], 0, 0, 0); __builtin_amdgcn_s_setprio(0); } while (0)
; #define PG8_WAIT_V(n) asm volatile("s_waitcnt vmcnt(" #n ")" ::: "memory")
; #define PG8_WAIT_L(n) asm volatile("s_waitcnt lgkmcnt(" #n ")" ::: "memory")
; #define PG8_BAR __builtin_amdgcn_s_barrier()
; #define PG8_SCHED __builtin_amdgcn_sched_barrier(0)
; template <class Epi, class Sched>
; __device__ __forceinline__ void gemm_phase(const int tid, LAS unsigned char* lds, const bf16* Aop, const bf16* Bop, const int K_, const Sched& S, const Epi& E, const bf16* Aop1 = nullptr, const bf16* Bop1 = nullptr) {
;     ...
;             PG8_LDA(At, 1, 1); PG8_STAGE(PG8_SB(1, 0), b3, voffB); PG8_STAGE(PG8_SB(1, 1), b3 + hstep, voffB); PG8_STAGE(PG8_SA(1, 0), a3, voffA[0]);
;             PG8_WAIT_V(8); PG8_WAIT_L(0); PG8_BAR; PG8_MMA(1, 0, At, B0); PG8_MMA(1, 1, At, B1); PG8_BAR; PG8_SCHED;
;         }
	s_add_i32 s36, s69, s52
	v_lshl_add_u64 v[194:195], v[194:195], 0, s[20:21]
	s_mov_b32 m0, s36
	ds_read_b128 v[178:181], v144 offset:49152
	ds_read_b128 v[182:185], v144 offset:50176
	ds_read_b128 v[186:189], v144 offset:51200
	ds_read_b128 v[190:193], v144 offset:52224
	ds_read_b128 v[202:205], v144 offset:53248
	ds_read_b128 v[206:209], v144 offset:54272
	ds_read_b128 v[210:213], v144 offset:55296
	ds_read_b128 v[214:217], v144 offset:56320
	global_load_lds_dwordx4 v[194:195], off
	v_lshl_add_u64 v[194:195], v[196:197], 0, s[20:21]
	s_add_i32 m0, s36, 0x2000
	s_add_i32 s36, s70, s52
	global_load_lds_dwordx4 v[194:195], off
	v_lshl_add_u64 v[194:195], v[198:199], 0, s[20:21]
	s_mov_b32 m0, s36
	s_nop 0
	global_load_lds_dwordx4 v[194:195], off
	v_lshl_add_u64 v[194:195], v[218:219], 0, s[20:21]
	s_add_i32 m0, s36, 0x2000
	s_nop 0
	global_load_lds_dwordx4 v[194:195], off
	v_lshl_add_u64 v[194:195], v[220:221], 0, s[20:21]
	s_mov_b32 m0, s59
	s_nop 0
	global_load_lds_dwordx4 v[194:195], off
	v_lshl_add_u64 v[194:195], v[222:223], 0, s[20:21]
	s_mov_b32 m0, s60
	s_nop 0
	global_load_lds_dwordx4 v[194:195], off
	s_waitcnt vmcnt(8)
	s_waitcnt lgkmcnt(0)
	s_barrier
	s_setprio 1
	s_waitcnt lgkmcnt(0)
	v_mfma_f32_16x16x32_bf16 v[64:67], v[146:149], v[178:181], v[64:67]
	v_mfma_f32_16x16x32_bf16 v[60:63], v[154:157], v[178:181], v[60:63]
	v_mfma_f32_16x16x32_bf16 v[48:51], v[146:149], v[186:189], v[48:51]
	v_mfma_f32_16x16x32_bf16 v[44:47], v[154:157], v[186:189], v[44:47]
	v_mfma_f32_16x16x32_bf16 v[32:35], v[146:149], v[202:205], v[32:35]
	v_mfma_f32_16x16x32_bf16 v[28:31], v[154:157], v[202:205], v[28:31]
	v_mfma_f32_16x16x32_bf16 v[16:19], v[146:149], v[210:213], v[16:19]
	v_mfma_f32_16x16x32_bf16 v[12:15], v[154:157], v[210:213], v[12:15]
	v_mfma_f32_16x16x32_bf16 v[64:67], v[150:153], v[182:185], v[64:67]
	v_mfma_f32_16x16x32_bf16 v[60:63], v[158:161], v[182:185], v[60:63]
	v_mfma_f32_16x16x32_bf16 v[48:51], v[150:153], v[190:193], v[48:51]
	v_mfma_f32_16x16x32_bf16 v[44:47], v[158:161], v[190:193], v[44:47]
	v_mfma_f32_16x16x32_bf16 v[32:35], v[150:153], v[206:209], v[32:35]
	v_mfma_f32_16x16x32_bf16 v[28:31], v[158:161], v[206:209], v[28:31]
	v_mfma_f32_16x16x32_bf16 v[16:19], v[150:153], v[214:217], v[16:19]
	v_mfma_f32_16x16x32_bf16 v[12:15], v[158:161], v[214:217], v[12:15]
	s_setprio 0
	s_setprio 1
	v_mfma_f32_16x16x32_bf16 v[56:59], v[162:165], v[178:181], v[56:59]
	v_mfma_f32_16x16x32_bf16 v[52:55], v[170:173], v[178:181], v[52:55]
	v_mfma_f32_16x16x32_bf16 v[40:43], v[162:165], v[186:189], v[40:43]
	v_mfma_f32_16x16x32_bf16 v[36:39], v[170:173], v[186:189], v[36:39]
	v_mfma_f32_16x16x32_bf16 v[24:27], v[162:165], v[202:205], v[24:27]
	v_mfma_f32_16x16x32_bf16 v[20:23], v[170:173], v[202:205], v[20:23]
	v_mfma_f32_16x16x32_bf16 v[8:11], v[162:165], v[210:213], v[8:11]
	v_mfma_f32_16x16x32_bf16 v[4:7], v[170:173], v[210:213], v[4:7]
	v_mfma_f32_16x16x32_bf16 v[56:59], v[166:169], v[182:185], v[56:59]
	v_mfma_f32_16x16x32_bf16 v[52:55], v[174:177], v[182:185], v[52:55]
	v_mfma_f32_16x16x32_bf16 v[40:43], v[166:169], v[190:193], v[40:43]
	v_mfma_f32_16x16x32_bf16 v[36:39], v[174:177], v[190:193], v[36:39]
	v_mfma_f32_16x16x32_bf16 v[24:27], v[166:169], v[206:209], v[24:27]
	v_mfma_f32_16x16x32_bf16 v[20:23], v[174:177], v[206:209], v[20:23]
	v_mfma_f32_16x16x32_bf16 v[8:11], v[166:169], v[214:217], v[8:11]
	v_mfma_f32_16x16x32_bf16 v[4:7], v[174:177], v[214:217], v[4:7]
	s_setprio 0
	s_barrier
	s_add_u32 s34, s34, 0x100
	s_addc_u32 s35, s35, 0
	s_add_u32 s15, s15, 0x100
	s_addc_u32 s67, s67, 0
	s_cmp_ge_i32 s68, s58
	s_mov_b32 s36, s68
	s_cbranch_scc0 .LBB0_1420
	s_branch .LBB0_1421

; #define PG8_GOFFS(slot_) do { _Pragma("unroll") for (int _i = 0; _i < 2; ++_i) { int R, C; stage_rc(tid * 16 + _i * 8192, R, C); _Pragma("unroll") for (int _h = 0; _h < 2; ++_h) { \
;         unsigned t_ = gtab[(slot_) * 256 + R + 128 * _h]; t_ = t_ < (unsigned)(T - 1) ? t_ : (unsigned)(T - 1); voffA[_h][_i] = (t_ * (unsigned)K + (unsigned)C) * 2u; } } } while (0)
; #define PG8_STAGE(bufoff, gbase, voff) do { _Pragma("unroll") for (int _i = 0; _i < 2; ++_i) \
;         __builtin_amdgcn_global_load_lds((const unsigned*)((const char*)(gbase) + (voff)[_i]), (LAS unsigned*)(lds + (bufoff) + ldsw + _i * 8192), 16, 0, 0); } while (0)
; #define PG8_STAGE_A1(bufoff, gbase) do { if (Epi::GATHER) PG8_STAGE(bufoff, gbase, voffA[1]); else PG8_STAGE(bufoff, (gbase) + hstep, voffA[0]); } while (0)
; #define PG8_LDA(dst, b, h) do { _Pragma("unroll") for (int m = 0; m < 4; ++m) _Pragma("unroll") for (int k = 0; k < 2; ++k) dst[m][k] = *(const LAS bf16x8*)(lds + PG8_SA(b, h) + aoff + m * 2048 + k * 1024); } while (0)
; #define PG8_WAIT_V(n) asm volatile("s_waitcnt vmcnt(" #n ")" ::: "memory")
; #define PG8_WAIT_L(n) asm volatile("s_waitcnt lgkmcnt(" #n ")" ::: "memory")
; #define PG8_BAR __builtin_amdgcn_s_barrier()
; template <class Epi, class Sched>
; __device__ __forceinline__ void gemm_phase(const int tid, LAS unsigned char* lds, const bf16* Aop, const bf16* Bop, const int K_, const Sched& S, const Epi& E, const bf16* Aop1 = nullptr, const bf16* Bop1 = nullptr) {
;     ...
;         for (int t = 0; t < nt; t += 2) {
;             const bool last = (t == nt - 2);
;             const char* a1 = cA + (size_t)(t + 1) * kstep;
;             const char* a2 = last ? nA : cA + (size_t)(t + 2) * kstep; const char* b2 = last ? nB : cB + (size_t)(t + 2) * kstep;
;             const char* a3 = a2 + kstep; const char* b3 = b2 + kstep;
;             PG8_LDB(B0, 0, 0); PG8_LDB(B1, 0, 1); PG8_SCHED; PG8_LDA(At, 0, 0); PG8_STAGE_A1(PG8_SA(1, 1), a1);
;             PG8_WAIT_V(8); PG8_WAIT_L(0); PG8_BAR; PG8_MMA(0, 0, At, B0); PG8_MMA(0, 1, At, B1); PG8_BAR; PG8_SCHED;
;             PG8_LDA(At, 0, 1); PG8_STAGE(PG8_SB(0, 0), b2, voffB); PG8_STAGE(PG8_SB(0, 1), b2 + hstep, voffB); if (Epi::GATHER && last && has_next) PG8_GOFFS((ui + 1) & 1); PG8_STAGE(PG8_SA(0, 0), a2, voffA[0]);
;             PG8_WAIT_V(8); PG8_WAIT_L(0); PG8_BAR; PG8_MMA(1, 0, At, B0); PG8_MMA(1, 1, At, B1); PG8_BAR; PG8_SCHED;
.LBB0_1595:
	v_mov_b32_e32 v131, 0
	s_andn2_b64 vcc, exec, s[64:65]
	s_cbranch_vccnz .LBB0_1598
	s_add_u32 s2, s2, 0x80
	s_addc_u32 s3, s3, 0
	s_add_u32 s6, s4, 0x100
	s_addc_u32 s7, s5, 0
	s_mov_b32 s4, 0
	s_add_i32 s72, s4, 2
	s_add_u32 s73, s2, 0x80
	s_addc_u32 s5, s3, 0
	s_add_i32 s76, 0, 0x10000
	s_cmp_eq_u32 s37, s4
	s_cselect_b32 s5, s41, s5
	s_cselect_b32 s4, s40, s73
	v_add_u32_e32 v158, s76, v160
	s_cselect_b32 s75, s69, s7
	s_cselect_b32 s74, s68, s6
	s_add_i32 s73, 0, 0x14000
	ds_read_b128 v[132:135], v158
	ds_read_b128 v[136:139], v158 offset:1024
	ds_read_b128 v[154:157], v158 offset:2048
	ds_read_b128 v[164:167], v158 offset:3072
	v_add_u32_e32 v158, s73, v160
	ds_read_b128 v[168:171], v158
	ds_read_b128 v[172:175], v158 offset:1024
	ds_read_b128 v[176:179], v158 offset:2048
	ds_read_b128 v[180:183], v158 offset:3072
	v_lshl_add_u64 v[158:159], s[2:3], 0, v[150:151]
	s_add_i32 m0, s17, 0xc000
	ds_read_b128 v[184:187], v162
	ds_read_b128 v[188:191], v162 offset:1024
	ds_read_b128 v[192:195], v162 offset:2048
	ds_read_b128 v[202:205], v162 offset:3072
	ds_read_b128 v[206:209], v162 offset:4096
	ds_read_b128 v[210:213], v162 offset:5120
	ds_read_b128 v[214:217], v162 offset:6144
	ds_read_b128 v[218:221], v162 offset:7168
	global_load_lds_dwordx4 v[158:159], off
	v_lshl_add_u64 v[158:159], s[2:3], 0, v[152:153]
	s_add_i32 m0, s17, 0xe000
	s_nop 0
	global_load_lds_dwordx4 v[158:159], off
	s_waitcnt vmcnt(8)
	s_waitcnt lgkmcnt(0)
	s_barrier
	s_setprio 1
	s_waitcnt lgkmcnt(0)
	v_mfma_f32_16x16x32_bf16 v[128:131], v[132:135], v[184:187], 0
	v_mfma_f32_16x16x32_bf16 v[124:127], v[154:157], v[184:187], 0
	v_mfma_f32_16x16x32_bf16 v[112:115], v[132:135], v[192:195], 0
	v_mfma_f32_16x16x32_bf16 v[108:111], v[154:157], v[192:195], 0
	v_mfma_f32_16x16x32_bf16 v[96:99], v[132:135], v[206:209], 0
	v_mfma_f32_16x16x32_bf16 v[92:95], v[154:157], v[206:209], 0
	v_mfma_f32_16x16x32_bf16 v[80:83], v[132:135], v[214:217], 0
	v_mfma_f32_16x16x32_bf16 v[76:79], v[154:157], v[214:217], 0
	v_mfma_f32_16x16x32_bf16 v[128:131], v[136:139], v[188:191], v[128:131]
	v_mfma_f32_16x16x32_bf16 v[124:127], v[164:167], v[188:191], v[124:127]
	v_mfma_f32_16x16x32_bf16 v[112:115], v[136:139], v[202:205], v[112:115]
	v_mfma_f32_16x16x32_bf16 v[108:111], v[164:167], v[202:205], v[108:111]
	v_mfma_f32_16x16x32_bf16 v[96:99], v[136:139], v[210:213], v[96:99]
	v_mfma_f32_16x16x32_bf16 v[92:95], v[164:167], v[210:213], v[92:95]
	v_mfma_f32_16x16x32_bf16 v[80:83], v[136:139], v[218:221], v[80:83]
	v_mfma_f32_16x16x32_bf16 v[76:79], v[164:167], v[218:221], v[76:79]
	s_setprio 0
	s_setprio 1
	v_mfma_f32_16x16x32_bf16 v[120:123], v[168:171], v[184:187], 0
	v_mfma_f32_16x16x32_bf16 v[116:119], v[176:179], v[184:187], 0
	v_mfma_f32_16x16x32_bf16 v[104:107], v[168:171], v[192:195], 0
	v_mfma_f32_16x16x32_bf16 v[100:103], v[176:179], v[192:195], 0
	v_mfma_f32_16x16x32_bf16 v[88:91], v[168:171], v[206:209], 0
	v_mfma_f32_16x16x32_bf16 v[84:87], v[176:179], v[206:209], 0
	v_mfma_f32_16x16x32_bf16 v[72:75], v[168:171], v[214:217], 0
	v_mfma_f32_16x16x32_bf16 v[68:71], v[176:179], v[214:217], 0
	v_mfma_f32_16x16x32_bf16 v[120:123], v[172:175], v[188:191], v[120:123]
	v_mfma_f32_16x16x32_bf16 v[116:119], v[180:183], v[188:191], v[116:119]
	v_mfma_f32_16x16x32_bf16 v[104:107], v[172:175], v[202:205], v[104:107]
	v_mfma_f32_16x16x32_bf16 v[100:103], v[180:183], v[202:205], v[100:103]
	v_mfma_f32_16x16x32_bf16 v[88:91], v[172:175], v[210:213], v[88:91]
	v_mfma_f32_16x16x32_bf16 v[84:87], v[180:183], v[210:213], v[84:87]
	v_mfma_f32_16x16x32_bf16 v[72:75], v[172:175], v[218:221], v[72:75]
	v_mfma_f32_16x16x32_bf16 v[68:71], v[180:183], v[218:221], v[68:71]
	s_setprio 0
	s_barrier
	s_add_i32 s76, s76, s16
	v_lshl_add_u64 v[158:159], s[74:75], 0, v[142:143]
	s_mov_b32 m0, s76
	ds_read_b128 v[184:187], v162 offset:16384
	ds_read_b128 v[188:191], v162 offset:17408
	ds_read_b128 v[192:195], v162 offset:18432
	ds_read_b128 v[202:205], v162 offset:19456
	ds_read_b128 v[206:209], v162 offset:20480
	ds_read_b128 v[210:213], v162 offset:21504
	ds_read_b128 v[214:217], v162 offset:22528
	ds_read_b128 v[218:221], v162 offset:23552
	global_load_lds_dwordx4 v[158:159], off
	s_add_i32 m0, s76, 0x2000
	v_lshl_add_u64 v[196:197], s[74:75], 0, v[146:147]
	s_add_u32 s74, s74, s58
	s_addc_u32 s75, s75, s59
	s_add_i32 s73, s73, s16
	global_load_lds_dwordx4 v[196:197], off
	v_lshl_add_u64 v[198:199], s[74:75], 0, v[142:143]
	s_mov_b32 m0, s73
	v_lshl_add_u64 v[222:223], s[74:75], 0, v[146:147]
	global_load_lds_dwordx4 v[198:199], off
	s_add_i32 m0, s73, 0x2000
	v_lshl_add_u64 v[224:225], s[4:5], 0, v[140:141]
	global_load_lds_dwordx4 v[222:223], off
	s_mov_b32 m0, s17
	v_lshl_add_u64 v[230:231], s[4:5], 0, v[144:145]
	global_load_lds_dwordx4 v[224:225], off
	s_mov_b32 m0, s28
	s_nop 0
	global_load_lds_dwordx4 v[230:231], off
	s_waitcnt vmcnt(8)
	s_waitcnt lgkmcnt(0)
	s_barrier
; #define PG8_STAGE_A1(bufoff, gbase) do { if (Epi::GATHER) PG8_STAGE(bufoff, gbase, voffA[1]); else PG8_STAGE(bufoff, (gbase) + hstep, voffA[0]); } while (0)
; #define PG8_LDA(dst, b, h) do { _Pragma("unroll") for (int m = 0; m < 4; ++m) _Pragma("unroll") for (int k = 0; k < 2; ++k) dst[m][k] = *(const LAS bf16x8*)(lds + PG8_SA(b, h) + aoff + m * 2048 + k * 1024); } while (0)
; #define PG8_LDB(dst, b, h) do { _Pragma("unroll") for (int n = 0; n < 2; ++n) _Pragma("unroll") for (int k = 0; k < 2; ++k) dst[n][k] = *(const LAS bf16x8*)(lds + PG8_SB(b, h) + boff + n * 2048 + k * 1024); } while (0)
; #define PG8_MMA(ai, bj, At, Bt) do { __builtin_amdgcn_s_setprio(1); _Pragma("unroll") for (int m = 0; m < 4; ++m) _Pragma("unroll") for (int n = 0; n < 2; ++n) _Pragma("unroll") for (int k = 0; k < 2; ++k) \
;         acc[ai][bj][m][n] = __builtin_amdgcn_mfma_f32_16x16x32_bf16(Bt[n][k], At[m][k], acc[ai][bj][m][n], 0, 0, 0); __builtin_amdgcn_s_setprio(0); } while (0)
; #define PG8_WAIT_V(n) asm volatile("s_waitcnt vmcnt(" #n ")" ::: "memory")
; #define PG8_WAIT_L(n) asm volatile("s_waitcnt lgkmcnt(" #n ")" ::: "memory")
; #define PG8_BAR __builtin_amdgcn_s_barrier()
; #define PG8_SCHED __builtin_amdgcn_sched_barrier(0)
; template <class Epi, class Sched>
; __device__ __forceinline__ void gemm_phase(const int tid, LAS unsigned char* lds, const bf16* Aop, const bf16* Bop, const int K_, const Sched& S, const Epi& E, const bf16* Aop1 = nullptr, const bf16* Bop1 = nullptr) {
;     ...
;             PG8_WAIT_V(8); PG8_WAIT_L(0); PG8_BAR; PG8_MMA(1, 0, At, B0); PG8_MMA(1, 1, At, B1); PG8_BAR; PG8_SCHED;
;             PG8_LDB(B0, 1, 0); PG8_LDB(B1, 1, 1); PG8_SCHED; PG8_LDA(At, 1, 0); PG8_STAGE_A1(PG8_SA(0, 1), a2);
;             PG8_WAIT_V(8); PG8_WAIT_L(0); PG8_BAR; PG8_MMA(0, 0, At, B0); PG8_MMA(0, 1, At, B1); PG8_BAR; PG8_SCHED;
	s_setprio 1
	s_waitcnt lgkmcnt(0)
	v_mfma_f32_16x16x32_bf16 v[64:67], v[132:135], v[184:187], 0
	v_mfma_f32_16x16x32_bf16 v[60:63], v[154:157], v[184:187], 0
	v_mfma_f32_16x16x32_bf16 v[48:51], v[132:135], v[192:195], 0
	v_mfma_f32_16x16x32_bf16 v[44:47], v[154:157], v[192:195], 0
	v_mfma_f32_16x16x32_bf16 v[32:35], v[132:135], v[206:209], 0
	v_mfma_f32_16x16x32_bf16 v[28:31], v[154:157], v[206:209], 0
	v_mfma_f32_16x16x32_bf16 v[16:19], v[132:135], v[214:217], 0
	v_mfma_f32_16x16x32_bf16 v[12:15], v[154:157], v[214:217], 0
	v_mfma_f32_16x16x32_bf16 v[64:67], v[136:139], v[188:191], v[64:67]
	v_mfma_f32_16x16x32_bf16 v[60:63], v[164:167], v[188:191], v[60:63]
	v_mfma_f32_16x16x32_bf16 v[48:51], v[136:139], v[202:205], v[48:51]
	v_mfma_f32_16x16x32_bf16 v[44:47], v[164:167], v[202:205], v[44:47]
	v_mfma_f32_16x16x32_bf16 v[32:35], v[136:139], v[210:213], v[32:35]
	v_mfma_f32_16x16x32_bf16 v[28:31], v[164:167], v[210:213], v[28:31]
	v_mfma_f32_16x16x32_bf16 v[16:19], v[136:139], v[218:221], v[16:19]
	v_mfma_f32_16x16x32_bf16 v[12:15], v[164:167], v[218:221], v[12:15]
	s_setprio 0
	s_setprio 1
	v_mfma_f32_16x16x32_bf16 v[56:59], v[168:171], v[184:187], 0
	v_mfma_f32_16x16x32_bf16 v[52:55], v[176:179], v[184:187], 0
	v_mfma_f32_16x16x32_bf16 v[40:43], v[168:171], v[192:195], 0
	v_mfma_f32_16x16x32_bf16 v[36:39], v[176:179], v[192:195], 0
	v_mfma_f32_16x16x32_bf16 v[24:27], v[168:171], v[206:209], 0
	v_mfma_f32_16x16x32_bf16 v[20:23], v[176:179], v[206:209], 0
	v_mfma_f32_16x16x32_bf16 v[8:11], v[168:171], v[214:217], 0
	v_mfma_f32_16x16x32_bf16 v[4:7], v[176:179], v[214:217], 0
	v_mfma_f32_16x16x32_bf16 v[56:59], v[172:175], v[188:191], v[56:59]
	v_mfma_f32_16x16x32_bf16 v[52:55], v[180:183], v[188:191], v[52:55]
	v_mfma_f32_16x16x32_bf16 v[40:43], v[172:175], v[202:205], v[40:43]
	v_mfma_f32_16x16x32_bf16 v[36:39], v[180:183], v[202:205], v[36:39]
	v_mfma_f32_16x16x32_bf16 v[24:27], v[172:175], v[210:213], v[24:27]
	v_mfma_f32_16x16x32_bf16 v[20:23], v[180:183], v[210:213], v[20:23]
	v_mfma_f32_16x16x32_bf16 v[8:11], v[172:175], v[218:221], v[8:11]
	v_mfma_f32_16x16x32_bf16 v[4:7], v[180:183], v[218:221], v[4:7]
	s_setprio 0
	s_barrier
	s_add_i32 s73, 0, 0x18000
	v_add_u32_e32 v163, s73, v160
	s_add_i32 s74, 0, 0x1c000
	ds_read_b128 v[132:135], v163
	ds_read_b128 v[136:139], v163 offset:1024
	ds_read_b128 v[154:157], v163 offset:2048
	ds_read_b128 v[164:167], v163 offset:3072
	v_add_u32_e32 v163, s74, v160
	ds_read_b128 v[168:171], v163
	ds_read_b128 v[172:175], v163 offset:1024
	ds_read_b128 v[176:179], v163 offset:2048
	ds_read_b128 v[180:183], v163 offset:3072
	s_add_u32 s4, s4, s58
	s_addc_u32 s5, s5, s59
	s_mov_b32 m0, s29
	v_lshl_add_u64 v[232:233], s[4:5], 0, v[140:141]
	ds_read_b128 v[184:187], v162 offset:32768
	ds_read_b128 v[188:191], v162 offset:33792
	ds_read_b128 v[192:195], v162 offset:34816
	ds_read_b128 v[202:205], v162 offset:35840
	ds_read_b128 v[206:209], v162 offset:36864
	ds_read_b128 v[210:213], v162 offset:37888
	ds_read_b128 v[214:217], v162 offset:38912
	ds_read_b128 v[218:221], v162 offset:39936
	global_load_lds_dwordx4 v[232:233], off
	v_lshl_add_u64 v[232:233], s[4:5], 0, v[144:145]
	s_mov_b32 m0, s34
	s_nop 0
	global_load_lds_dwordx4 v[232:233], off
	s_waitcnt vmcnt(8)
	s_waitcnt lgkmcnt(0)
	s_barrier
	s_setprio 1
	s_waitcnt lgkmcnt(0)
	v_mfma_f32_16x16x32_bf16 v[128:131], v[132:135], v[184:187], v[128:131]
	v_mfma_f32_16x16x32_bf16 v[124:127], v[154:157], v[184:187], v[124:127]
	v_mfma_f32_16x16x32_bf16 v[112:115], v[132:135], v[192:195], v[112:115]
	v_mfma_f32_16x16x32_bf16 v[108:111], v[154:157], v[192:195], v[108:111]
	v_mfma_f32_16x16x32_bf16 v[96:99], v[132:135], v[206:209], v[96:99]
	v_mfma_f32_16x16x32_bf16 v[92:95], v[154:157], v[206:209], v[92:95]
	v_mfma_f32_16x16x32_bf16 v[80:83], v[132:135], v[214:217], v[80:83]
	v_mfma_f32_16x16x32_bf16 v[76:79], v[154:157], v[214:217], v[76:79]
	v_mfma_f32_16x16x32_bf16 v[128:131], v[136:139], v[188:191], v[128:131]
	v_mfma_f32_16x16x32_bf16 v[124:127], v[164:167], v[188:191], v[124:127]
	v_mfma_f32_16x16x32_bf16 v[112:115], v[136:139], v[202:205], v[112:115]
	v_mfma_f32_16x16x32_bf16 v[108:111], v[164:167], v[202:205], v[108:111]
	v_mfma_f32_16x16x32_bf16 v[96:99], v[136:139], v[210:213], v[96:99]
	v_mfma_f32_16x16x32_bf16 v[92:95], v[164:167], v[210:213], v[92:95]
	v_mfma_f32_16x16x32_bf16 v[80:83], v[136:139], v[218:221], v[80:83]
	v_mfma_f32_16x16x32_bf16 v[76:79], v[164:167], v[218:221], v[76:79]
	s_setprio 0
	s_setprio 1
	v_mfma_f32_16x16x32_bf16 v[120:123], v[168:171], v[184:187], v[120:123]
	v_mfma_f32_16x16x32_bf16 v[116:119], v[176:179], v[184:187], v[116:119]
	v_mfma_f32_16x16x32_bf16 v[104:107], v[168:171], v[192:195], v[104:107]
	v_mfma_f32_16x16x32_bf16 v[100:103], v[176:179], v[192:195], v[100:103]
	v_mfma_f32_16x16x32_bf16 v[88:91], v[168:171], v[206:209], v[88:91]
	v_mfma_f32_16x16x32_bf16 v[84:87], v[176:179], v[206:209], v[84:87]
	v_mfma_f32_16x16x32_bf16 v[72:75], v[168:171], v[214:217], v[72:75]
	v_mfma_f32_16x16x32_bf16 v[68:71], v[176:179], v[214:217], v[68:71]
	v_mfma_f32_16x16x32_bf16 v[120:123], v[172:175], v[188:191], v[120:123]
	v_mfma_f32_16x16x32_bf16 v[116:119], v[180:183], v[188:191], v[116:119]
	v_mfma_f32_16x16x32_bf16 v[104:107], v[172:175], v[202:205], v[104:107]
	v_mfma_f32_16x16x32_bf16 v[100:103], v[180:183], v[202:205], v[100:103]
	v_mfma_f32_16x16x32_bf16 v[88:91], v[172:175], v[210:213], v[88:91]
	v_mfma_f32_16x16x32_bf16 v[84:87], v[180:183], v[210:213], v[84:87]
	v_mfma_f32_16x16x32_bf16 v[72:75], v[172:175], v[218:221], v[72:75]
	v_mfma_f32_16x16x32_bf16 v[68:71], v[180:183], v[218:221], v[68:71]
	s_setprio 0
	s_barrier
; #define PG8_STAGE(bufoff, gbase, voff) do { _Pragma("unroll") for (int _i = 0; _i < 2; ++_i) \
;         __builtin_amdgcn_global_load_lds((const unsigned*)((const char*)(gbase) + (voff)[_i]), (LAS unsigned*)(lds + (bufoff) + ldsw + _i * 8192), 16, 0, 0); } while (0)
; #define PG8_LDA(dst, b, h) do { _Pragma("unroll") for (int m = 0; m < 4; ++m) _Pragma("unroll") for (int k = 0; k < 2; ++k) dst[m][k] = *(const LAS bf16x8*)(lds + PG8_SA(b, h) + aoff + m * 2048 + k * 1024); } while (0)
; #define PG8_MMA(ai, bj, At, Bt) do { __builtin_amdgcn_s_setprio(1); _Pragma("unroll") for (int m = 0; m < 4; ++m) _Pragma("unroll") for (int n = 0; n < 2; ++n) _Pragma("unroll") for (int k = 0; k < 2; ++k) \
;         acc[ai][bj][m][n] = __builtin_amdgcn_mfma_f32_16x16x32_bf16(Bt[n][k], At[m][k], acc[ai][bj][m][n], 0, 0, 0); __builtin_amdgcn_s_setprio(0); } while (0)
; #define PG8_WAIT_V(n) asm volatile("s_waitcnt vmcnt(" #n ")" ::: "memory")
; #define PG8_WAIT_L(n) asm volatile("s_waitcnt lgkmcnt(" #n ")" ::: "memory")
; #define PG8_BAR __builtin_amdgcn_s_barrier()
; #define PG8_SCHED __builtin_amdgcn_sched_barrier(0)
; template <class Epi, class Sched>
; __device__ __forceinline__ void gemm_phase(const int tid, LAS unsigned char* lds, const bf16* Aop, const bf16* Bop, const int K_, const Sched& S, const Epi& E, const bf16* Aop1 = nullptr, const bf16* Bop1 = nullptr) {
;     ...
;             PG8_LDA(At, 1, 1); PG8_STAGE(PG8_SB(1, 0), b3, voffB); PG8_STAGE(PG8_SB(1, 1), b3 + hstep, voffB); PG8_STAGE(PG8_SA(1, 0), a3, voffA[0]);
;             PG8_WAIT_V(8); PG8_WAIT_L(0); PG8_BAR; PG8_MMA(1, 0, At, B0); PG8_MMA(1, 1, At, B1); PG8_BAR; PG8_SCHED;
;         }
	s_add_i32 s4, s73, s16
	v_lshl_add_u64 v[158:159], v[158:159], 0, s[20:21]
	s_mov_b32 m0, s4
	ds_read_b128 v[184:187], v162 offset:49152
	ds_read_b128 v[188:191], v162 offset:50176
	ds_read_b128 v[192:195], v162 offset:51200
	ds_read_b128 v[202:205], v162 offset:52224
	ds_read_b128 v[206:209], v162 offset:53248
	ds_read_b128 v[210:213], v162 offset:54272
	ds_read_b128 v[214:217], v162 offset:55296
	ds_read_b128 v[218:221], v162 offset:56320
	global_load_lds_dwordx4 v[158:159], off
	v_lshl_add_u64 v[158:159], v[196:197], 0, s[20:21]
	s_add_i32 m0, s4, 0x2000
	s_add_i32 s4, s74, s16
	global_load_lds_dwordx4 v[158:159], off
	v_lshl_add_u64 v[158:159], v[198:199], 0, s[20:21]
	s_mov_b32 m0, s4
	s_nop 0
	global_load_lds_dwordx4 v[158:159], off
	v_lshl_add_u64 v[158:159], v[222:223], 0, s[20:21]
	s_add_i32 m0, s4, 0x2000
	s_nop 0
	global_load_lds_dwordx4 v[158:159], off
	v_lshl_add_u64 v[158:159], v[224:225], 0, s[20:21]
	s_mov_b32 m0, s35
	s_nop 0
	global_load_lds_dwordx4 v[158:159], off
	v_lshl_add_u64 v[158:159], v[230:231], 0, s[20:21]
	s_mov_b32 m0, s36
	s_nop 0
	global_load_lds_dwordx4 v[158:159], off
	s_waitcnt vmcnt(8)
	s_waitcnt lgkmcnt(0)
	s_barrier
	s_setprio 1
	s_waitcnt lgkmcnt(0)
	v_mfma_f32_16x16x32_bf16 v[64:67], v[132:135], v[184:187], v[64:67]
	v_mfma_f32_16x16x32_bf16 v[60:63], v[154:157], v[184:187], v[60:63]
	v_mfma_f32_16x16x32_bf16 v[48:51], v[132:135], v[192:195], v[48:51]
	v_mfma_f32_16x16x32_bf16 v[44:47], v[154:157], v[192:195], v[44:47]
	v_mfma_f32_16x16x32_bf16 v[32:35], v[132:135], v[206:209], v[32:35]
	v_mfma_f32_16x16x32_bf16 v[28:31], v[154:157], v[206:209], v[28:31]
	v_mfma_f32_16x16x32_bf16 v[16:19], v[132:135], v[214:217], v[16:19]
	v_mfma_f32_16x16x32_bf16 v[12:15], v[154:157], v[214:217], v[12:15]
	v_mfma_f32_16x16x32_bf16 v[64:67], v[136:139], v[188:191], v[64:67]
	v_mfma_f32_16x16x32_bf16 v[60:63], v[164:167], v[188:191], v[60:63]
	v_mfma_f32_16x16x32_bf16 v[48:51], v[136:139], v[202:205], v[48:51]
	v_mfma_f32_16x16x32_bf16 v[44:47], v[164:167], v[202:205], v[44:47]
	v_mfma_f32_16x16x32_bf16 v[32:35], v[136:139], v[210:213], v[32:35]
	v_mfma_f32_16x16x32_bf16 v[28:31], v[164:167], v[210:213], v[28:31]
	v_mfma_f32_16x16x32_bf16 v[16:19], v[136:139], v[218:221], v[16:19]
	v_mfma_f32_16x16x32_bf16 v[12:15], v[164:167], v[218:221], v[12:15]
	s_setprio 0
	s_setprio 1
	v_mfma_f32_16x16x32_bf16 v[56:59], v[168:171], v[184:187], v[56:59]
	v_mfma_f32_16x16x32_bf16 v[52:55], v[176:179], v[184:187], v[52:55]
	v_mfma_f32_16x16x32_bf16 v[40:43], v[168:171], v[192:195], v[40:43]
	v_mfma_f32_16x16x32_bf16 v[36:39], v[176:179], v[192:195], v[36:39]
	v_mfma_f32_16x16x32_bf16 v[24:27], v[168:171], v[206:209], v[24:27]
	v_mfma_f32_16x16x32_bf16 v[20:23], v[176:179], v[206:209], v[20:23]
	v_mfma_f32_16x16x32_bf16 v[8:11], v[168:171], v[214:217], v[8:11]
	v_mfma_f32_16x16x32_bf16 v[4:7], v[176:179], v[214:217], v[4:7]
	v_mfma_f32_16x16x32_bf16 v[56:59], v[172:175], v[188:191], v[56:59]
	v_mfma_f32_16x16x32_bf16 v[52:55], v[180:183], v[188:191], v[52:55]
	v_mfma_f32_16x16x32_bf16 v[40:43], v[172:175], v[202:205], v[40:43]
	v_mfma_f32_16x16x32_bf16 v[36:39], v[180:183], v[202:205], v[36:39]
	v_mfma_f32_16x16x32_bf16 v[24:27], v[172:175], v[210:213], v[24:27]
	v_mfma_f32_16x16x32_bf16 v[20:23], v[180:183], v[210:213], v[20:23]
	v_mfma_f32_16x16x32_bf16 v[8:11], v[172:175], v[218:221], v[8:11]
	v_mfma_f32_16x16x32_bf16 v[4:7], v[180:183], v[218:221], v[4:7]
	s_setprio 0
	s_barrier
	s_add_u32 s2, s2, 0x100
	s_addc_u32 s3, s3, 0
	s_add_u32 s6, s6, 0x100
	s_addc_u32 s7, s7, 0
	s_cmp_ge_i32 s72, s8
	s_mov_b32 s4, s72
	s_cbranch_scc0 .LBB0_1597
	s_branch .LBB0_1598
